# pool_item fast path: all row loads of an item issued at once (saddr offsets, exec-masked warm-up rows); GEMM LDS-DMA saddr form; nt h stores in rowpass; rnn2 carry fold batched; BF16 epilogue rewritte
# speedup vs baseline: 1.0222x; 1.0222x over previous
; DI unsigned pk2(float lo, float hi) { f32x2 v = {lo, hi}; bf16x2_t b = __builtin_convertvector(v, bf16x2_t); return __builtin_bit_cast(unsigned, b); }
; DI float bflo(unsigned u) { return __uint_as_float(u << 16); }
; DI float bfhi(unsigned u) { return __uint_as_float(u & 0xffff0000u); }
; DI void pool_item(const bf16_t* P, bf16_t* pooled, int idx) {
;     const int cg8 = idx & 127, run = idx >> 7; const size_t row0 = (size_t)run * 8; const int t0 = (int)(row0 & (SEQ - 1));
;     const int ch = cg8 * 8, w = 2 << (ch >> 8);
;     const bf16_t* src = P + PC_P + ch;
;     float sum[8];
; #pragma unroll
;     for (int j = 0; j < 8; ++j) sum[j] = 0.f;
;     for (int k = 1; k < w; ++k) if (t0 - k >= 0) { const u32x4 x = *(const u32x4*)(src + (row0 - k) * DIN);
;         sum[0] += bflo(x.x); sum[1] += bfhi(x.x); sum[2] += bflo(x.y); sum[3] += bfhi(x.y); sum[4] += bflo(x.z); sum[5] += bfhi(x.z); sum[6] += bflo(x.w); sum[7] += bfhi(x.w); }
; #pragma unroll
;     for (int j = 0; j < 8; ++j) {
;         const int t = t0 + j; const u32x4 x = *(const u32x4*)(src + (row0 + j) * DIN);
;         const float cur[8] = {bflo(x.x), bfhi(x.x), bflo(x.y), bfhi(x.y), bflo(x.z), bfhi(x.z), bflo(x.w), bfhi(x.w)};
; #pragma unroll
;         for (int e = 0; e < 8; ++e) sum[e] += cur[e];
;         const float ic = __builtin_amdgcn_rcpf((float)(t + 1 < w ? t + 1 : w));
;         u32x4 o; o.x = pk2(sum[0] * ic - cur[0], sum[1] * ic - cur[1]); o.y = pk2(sum[2] * ic - cur[2], sum[3] * ic - cur[3]);
;         o.z = pk2(sum[4] * ic - cur[4], sum[5] * ic - cur[5]); o.w = pk2(sum[6] * ic - cur[6], sum[7] * ic - cur[7]);
;         *(u32x4*)(pooled + (row0 + j) * D + ch) = o;
;         if (t - w + 1 >= 0) { const u32x4 y = *(const u32x4*)(src + (row0 + j - w + 1) * DIN);
;             sum[0] -= bflo(y.x); sum[1] -= bfhi(y.x); sum[2] -= bflo(y.y); sum[3] -= bfhi(y.y); sum[4] -= bflo(y.z); sum[5] -= bfhi(y.z); sum[6] -= bflo(y.w); sum[7] -= bfhi(y.w); }
;     }
.LBB0_310:
	v_lshrrev_b32_e32 v36, 7, v22
	v_lshlrev_b32_e32 v37, 4, v22
	v_readfirstlane_b32 s7, v36
	v_and_b32_e32 v37, 0x7f0, v37
	s_and_b32 s0, s7, 0x3ff
	s_cmp_lt_u32 s0, 2
	s_cbranch_scc1 .Lpool_slow
	v_mul_u32_u24_e32 v38, 0x1e000, v36
	v_bfe_u32 v39, v22, 5, 2
	v_lshlrev_b32_e64 v39, v39, 2
	v_add_u32_e32 v38, v38, v37
	v_add_u32_e32 v40, -1, v39
	v_mul_u32_u24_e32 v40, 0x3c00, v40
	v_cvt_f32_u32_e32 v42, v39
	v_sub_u32_e32 v40, v38, v40
	v_rcp_iflag_f32_e32 v42, v42
	v_readfirstlane_b32 s16, v39
	v_lshlrev_b32_e32 v41, 14, v36
	s_mov_b64 s[0:1], exec
	s_mov_b32 s30, 0
	s_mov_b32 s31, -1
	v_add_u32_e32 v41, v41, v37
	s_and_b64 s[30:31], s[0:1], s[30:31]
	s_cmp_eq_u32 s16, 2
	s_cbranch_scc0 .Lpool_kind8
	v_add_u32_e32 v25, 0xffffc400, v38
	global_load_dwordx4 v[44:47], v25, s[42:43]
	s_mov_b64 exec, s[30:31]
	v_add_u32_e32 v25, 0xffff8800, v38
	global_load_dwordx4 v[48:51], v25, s[42:43]
	v_add_u32_e32 v25, 0xffff4c00, v38
	global_load_dwordx4 v[52:55], v25, s[42:43]
	s_mov_b64 exec, s[0:1]
	v_mov_b32_e32 v25, v38
	global_load_dwordx4 v[108:111], v25, s[42:43]
	v_mov_b32_e32 v25, v40
	global_load_dwordx4 v[176:179], v25, s[42:43]
	v_add_u32_e32 v25, 0x3c00, v38
	global_load_dwordx4 v[112:115], v25, s[42:43]
	v_add_u32_e32 v25, 0x3c00, v40
	global_load_dwordx4 v[180:183], v25, s[42:43]
	v_add_u32_e32 v25, 0x7800, v38
	global_load_dwordx4 v[116:119], v25, s[42:43]
	v_add_u32_e32 v25, 0x7800, v40
	global_load_dwordx4 v[184:187], v25, s[42:43]
	v_add_u32_e32 v25, 0xb400, v38
	global_load_dwordx4 v[120:123], v25, s[42:43]
	v_add_u32_e32 v25, 0xb400, v40
	global_load_dwordx4 v[188:191], v25, s[42:43]
	v_add_u32_e32 v25, 0xf000, v38
	global_load_dwordx4 v[124:127], v25, s[42:43]
	v_add_u32_e32 v25, 0xf000, v40
	global_load_dwordx4 v[192:195], v25, s[42:43]
	v_add_u32_e32 v25, 0x12c00, v38
	global_load_dwordx4 v[128:131], v25, s[42:43]
	v_add_u32_e32 v25, 0x12c00, v40
	global_load_dwordx4 v[196:199], v25, s[42:43]
	v_add_u32_e32 v25, 0x16800, v38
	global_load_dwordx4 v[132:135], v25, s[42:43]
	v_add_u32_e32 v25, 0x16800, v40
	global_load_dwordx4 v[200:203], v25, s[42:43]
	v_add_u32_e32 v25, 0x1a400, v38
	global_load_dwordx4 v[136:139], v25, s[42:43]
	v_mov_b64_e32 v[208:209], 0
	v_mov_b64_e32 v[210:211], 0
	v_mov_b64_e32 v[212:213], 0
	v_mov_b64_e32 v[214:215], 0
	s_waitcnt vmcnt(17)
	v_lshlrev_b32_e32 v216, 16, v44
	v_and_b32_e32 v217, 0xffff0000, v44
	v_lshlrev_b32_e32 v218, 16, v45
	v_and_b32_e32 v219, 0xffff0000, v45
	v_lshlrev_b32_e32 v220, 16, v46
	v_and_b32_e32 v221, 0xffff0000, v46
	v_lshlrev_b32_e32 v222, 16, v47
	v_and_b32_e32 v223, 0xffff0000, v47
	v_pk_add_f32 v[208:209], v[208:209], v[216:217]
	v_pk_add_f32 v[210:211], v[210:211], v[218:219]
	v_pk_add_f32 v[212:213], v[212:213], v[220:221]
	v_pk_add_f32 v[214:215], v[214:215], v[222:223]
	s_mov_b64 exec, s[30:31]
	s_waitcnt vmcnt(16)
	v_lshlrev_b32_e32 v216, 16, v48
	v_and_b32_e32 v217, 0xffff0000, v48
	v_lshlrev_b32_e32 v218, 16, v49
	v_and_b32_e32 v219, 0xffff0000, v49
	v_lshlrev_b32_e32 v220, 16, v50
	v_and_b32_e32 v221, 0xffff0000, v50
	v_lshlrev_b32_e32 v222, 16, v51
	v_and_b32_e32 v223, 0xffff0000, v51
	v_pk_add_f32 v[208:209], v[208:209], v[216:217]
	v_pk_add_f32 v[210:211], v[210:211], v[218:219]
	v_pk_add_f32 v[212:213], v[212:213], v[220:221]
	v_pk_add_f32 v[214:215], v[214:215], v[222:223]
	s_waitcnt vmcnt(15)
	v_lshlrev_b32_e32 v216, 16, v52
	v_and_b32_e32 v217, 0xffff0000, v52
	v_lshlrev_b32_e32 v218, 16, v53
	v_and_b32_e32 v219, 0xffff0000, v53
	v_lshlrev_b32_e32 v220, 16, v54
	v_and_b32_e32 v221, 0xffff0000, v54
	v_lshlrev_b32_e32 v222, 16, v55
	v_and_b32_e32 v223, 0xffff0000, v55
	v_pk_add_f32 v[208:209], v[208:209], v[216:217]
	v_pk_add_f32 v[210:211], v[210:211], v[218:219]
	v_pk_add_f32 v[212:213], v[212:213], v[220:221]
	v_pk_add_f32 v[214:215], v[214:215], v[222:223]
	s_mov_b64 exec, s[0:1]
	s_branch .Lpool_rows
.Lpool_kind8:
	v_add_u32_e32 v25, 0xffffc400, v38
	global_load_dwordx4 v[44:47], v25, s[42:43]
	v_add_u32_e32 v25, 0xffff8800, v38
	global_load_dwordx4 v[48:51], v25, s[42:43]
	v_add_u32_e32 v25, 0xffff4c00, v38
	global_load_dwordx4 v[52:55], v25, s[42:43]
	v_add_u32_e32 v25, 0xffff1000, v38
	global_load_dwordx4 v[56:59], v25, s[42:43]
	v_add_u32_e32 v25, 0xfffed400, v38
	global_load_dwordx4 v[60:63], v25, s[42:43]
	v_add_u32_e32 v25, 0xfffe9800, v38
	global_load_dwordx4 v[64:67], v25, s[42:43]
	v_add_u32_e32 v25, 0xfffe5c00, v38
	global_load_dwordx4 v[68:71], v25, s[42:43]
	s_mov_b64 exec, s[30:31]
	v_add_u32_e32 v25, 0xfffe2000, v38
	global_load_dwordx4 v[72:75], v25, s[42:43]
	v_add_u32_e32 v25, 0xfffde400, v38
	global_load_dwordx4 v[76:79], v25, s[42:43]
	v_add_u32_e32 v25, 0xfffda800, v38
	global_load_dwordx4 v[84:87], v25, s[42:43]
	v_add_u32_e32 v25, 0xfffd6c00, v38
	global_load_dwordx4 v[88:91], v25, s[42:43]
	v_add_u32_e32 v25, 0xfffd3000, v38
	global_load_dwordx4 v[92:95], v25, s[42:43]
	v_add_u32_e32 v25, 0xfffcf400, v38
	global_load_dwordx4 v[96:99], v25, s[42:43]
	v_add_u32_e32 v25, 0xfffcb800, v38
	global_load_dwordx4 v[100:103], v25, s[42:43]
	v_add_u32_e32 v25, 0xfffc7c00, v38
	global_load_dwordx4 v[104:107], v25, s[42:43]
	s_mov_b64 exec, s[0:1]
	v_mov_b32_e32 v25, v38
	global_load_dwordx4 v[108:111], v25, s[42:43]
	v_mov_b32_e32 v25, v40
	global_load_dwordx4 v[176:179], v25, s[42:43]
	v_add_u32_e32 v25, 0x3c00, v38
	global_load_dwordx4 v[112:115], v25, s[42:43]
	v_add_u32_e32 v25, 0x3c00, v40
	global_load_dwordx4 v[180:183], v25, s[42:43]
	v_add_u32_e32 v25, 0x7800, v38
	global_load_dwordx4 v[116:119], v25, s[42:43]
	v_add_u32_e32 v25, 0x7800, v40
	global_load_dwordx4 v[184:187], v25, s[42:43]
	v_add_u32_e32 v25, 0xb400, v38
	global_load_dwordx4 v[120:123], v25, s[42:43]
	v_add_u32_e32 v25, 0xb400, v40
	global_load_dwordx4 v[188:191], v25, s[42:43]
	v_add_u32_e32 v25, 0xf000, v38
	global_load_dwordx4 v[124:127], v25, s[42:43]
	v_add_u32_e32 v25, 0xf000, v40
	global_load_dwordx4 v[192:195], v25, s[42:43]
	v_add_u32_e32 v25, 0x12c00, v38
	global_load_dwordx4 v[128:131], v25, s[42:43]
	v_add_u32_e32 v25, 0x12c00, v40
	global_load_dwordx4 v[196:199], v25, s[42:43]
	v_add_u32_e32 v25, 0x16800, v38
	global_load_dwordx4 v[132:135], v25, s[42:43]
	v_add_u32_e32 v25, 0x16800, v40
	global_load_dwordx4 v[200:203], v25, s[42:43]
	v_add_u32_e32 v25, 0x1a400, v38
	global_load_dwordx4 v[136:139], v25, s[42:43]
	v_mov_b64_e32 v[208:209], 0
	v_mov_b64_e32 v[210:211], 0
	v_mov_b64_e32 v[212:213], 0
	v_mov_b64_e32 v[214:215], 0
	s_waitcnt vmcnt(29)
; DI float bflo(unsigned u) { return __uint_as_float(u << 16); }
; DI float bfhi(unsigned u) { return __uint_as_float(u & 0xffff0000u); }
; DI void pool_item(const bf16_t* P, bf16_t* pooled, int idx) {
;     ...
;     for (int k = 1; k < w; ++k) if (t0 - k >= 0) { const u32x4 x = *(const u32x4*)(src + (row0 - k) * DIN);
;         sum[0] += bflo(x.x); sum[1] += bfhi(x.x); sum[2] += bflo(x.y); sum[3] += bfhi(x.y); sum[4] += bflo(x.z); sum[5] += bfhi(x.z); sum[6] += bflo(x.w); sum[7] += bfhi(x.w); }
	v_lshlrev_b32_e32 v216, 16, v44
	v_and_b32_e32 v217, 0xffff0000, v44
	v_lshlrev_b32_e32 v218, 16, v45
	v_and_b32_e32 v219, 0xffff0000, v45
	v_lshlrev_b32_e32 v220, 16, v46
	v_and_b32_e32 v221, 0xffff0000, v46
	v_lshlrev_b32_e32 v222, 16, v47
	v_and_b32_e32 v223, 0xffff0000, v47
	v_pk_add_f32 v[208:209], v[208:209], v[216:217]
	v_pk_add_f32 v[210:211], v[210:211], v[218:219]
	v_pk_add_f32 v[212:213], v[212:213], v[220:221]
	v_pk_add_f32 v[214:215], v[214:215], v[222:223]
	s_waitcnt vmcnt(28)
	v_lshlrev_b32_e32 v216, 16, v48
	v_and_b32_e32 v217, 0xffff0000, v48
	v_lshlrev_b32_e32 v218, 16, v49
	v_and_b32_e32 v219, 0xffff0000, v49
	v_lshlrev_b32_e32 v220, 16, v50
	v_and_b32_e32 v221, 0xffff0000, v50
	v_lshlrev_b32_e32 v222, 16, v51
	v_and_b32_e32 v223, 0xffff0000, v51
	v_pk_add_f32 v[208:209], v[208:209], v[216:217]
	v_pk_add_f32 v[210:211], v[210:211], v[218:219]
	v_pk_add_f32 v[212:213], v[212:213], v[220:221]
	v_pk_add_f32 v[214:215], v[214:215], v[222:223]
	s_waitcnt vmcnt(27)
	v_lshlrev_b32_e32 v216, 16, v52
	v_and_b32_e32 v217, 0xffff0000, v52
	v_lshlrev_b32_e32 v218, 16, v53
	v_and_b32_e32 v219, 0xffff0000, v53
	v_lshlrev_b32_e32 v220, 16, v54
	v_and_b32_e32 v221, 0xffff0000, v54
	v_lshlrev_b32_e32 v222, 16, v55
	v_and_b32_e32 v223, 0xffff0000, v55
	v_pk_add_f32 v[208:209], v[208:209], v[216:217]
	v_pk_add_f32 v[210:211], v[210:211], v[218:219]
	v_pk_add_f32 v[212:213], v[212:213], v[220:221]
	v_pk_add_f32 v[214:215], v[214:215], v[222:223]
	s_waitcnt vmcnt(26)
	v_lshlrev_b32_e32 v216, 16, v56
	v_and_b32_e32 v217, 0xffff0000, v56
	v_lshlrev_b32_e32 v218, 16, v57
	v_and_b32_e32 v219, 0xffff0000, v57
	v_lshlrev_b32_e32 v220, 16, v58
	v_and_b32_e32 v221, 0xffff0000, v58
	v_lshlrev_b32_e32 v222, 16, v59
	v_and_b32_e32 v223, 0xffff0000, v59
	v_pk_add_f32 v[208:209], v[208:209], v[216:217]
	v_pk_add_f32 v[210:211], v[210:211], v[218:219]
	v_pk_add_f32 v[212:213], v[212:213], v[220:221]
	v_pk_add_f32 v[214:215], v[214:215], v[222:223]
	s_waitcnt vmcnt(25)
	v_lshlrev_b32_e32 v216, 16, v60
	v_and_b32_e32 v217, 0xffff0000, v60
	v_lshlrev_b32_e32 v218, 16, v61
	v_and_b32_e32 v219, 0xffff0000, v61
	v_lshlrev_b32_e32 v220, 16, v62
	v_and_b32_e32 v221, 0xffff0000, v62
	v_lshlrev_b32_e32 v222, 16, v63
	v_and_b32_e32 v223, 0xffff0000, v63
	v_pk_add_f32 v[208:209], v[208:209], v[216:217]
	v_pk_add_f32 v[210:211], v[210:211], v[218:219]
	v_pk_add_f32 v[212:213], v[212:213], v[220:221]
	v_pk_add_f32 v[214:215], v[214:215], v[222:223]
	s_waitcnt vmcnt(24)
	v_lshlrev_b32_e32 v216, 16, v64
	v_and_b32_e32 v217, 0xffff0000, v64
	v_lshlrev_b32_e32 v218, 16, v65
	v_and_b32_e32 v219, 0xffff0000, v65
	v_lshlrev_b32_e32 v220, 16, v66
	v_and_b32_e32 v221, 0xffff0000, v66
	v_lshlrev_b32_e32 v222, 16, v67
	v_and_b32_e32 v223, 0xffff0000, v67
	v_pk_add_f32 v[208:209], v[208:209], v[216:217]
	v_pk_add_f32 v[210:211], v[210:211], v[218:219]
	v_pk_add_f32 v[212:213], v[212:213], v[220:221]
	v_pk_add_f32 v[214:215], v[214:215], v[222:223]
	s_waitcnt vmcnt(23)
	v_lshlrev_b32_e32 v216, 16, v68
	v_and_b32_e32 v217, 0xffff0000, v68
	v_lshlrev_b32_e32 v218, 16, v69
	v_and_b32_e32 v219, 0xffff0000, v69
	v_lshlrev_b32_e32 v220, 16, v70
	v_and_b32_e32 v221, 0xffff0000, v70
	v_lshlrev_b32_e32 v222, 16, v71
	v_and_b32_e32 v223, 0xffff0000, v71
	v_pk_add_f32 v[208:209], v[208:209], v[216:217]
	v_pk_add_f32 v[210:211], v[210:211], v[218:219]
	v_pk_add_f32 v[212:213], v[212:213], v[220:221]
	v_pk_add_f32 v[214:215], v[214:215], v[222:223]
	s_mov_b64 exec, s[30:31]
	s_waitcnt vmcnt(22)
	v_lshlrev_b32_e32 v216, 16, v72
	v_and_b32_e32 v217, 0xffff0000, v72
	v_lshlrev_b32_e32 v218, 16, v73
	v_and_b32_e32 v219, 0xffff0000, v73
	v_lshlrev_b32_e32 v220, 16, v74
	v_and_b32_e32 v221, 0xffff0000, v74
	v_lshlrev_b32_e32 v222, 16, v75
	v_and_b32_e32 v223, 0xffff0000, v75
	v_pk_add_f32 v[208:209], v[208:209], v[216:217]
	v_pk_add_f32 v[210:211], v[210:211], v[218:219]
	v_pk_add_f32 v[212:213], v[212:213], v[220:221]
	v_pk_add_f32 v[214:215], v[214:215], v[222:223]
	s_waitcnt vmcnt(21)
	v_lshlrev_b32_e32 v216, 16, v76
	v_and_b32_e32 v217, 0xffff0000, v76
	v_lshlrev_b32_e32 v218, 16, v77
	v_and_b32_e32 v219, 0xffff0000, v77
	v_lshlrev_b32_e32 v220, 16, v78
	v_and_b32_e32 v221, 0xffff0000, v78
	v_lshlrev_b32_e32 v222, 16, v79
	v_and_b32_e32 v223, 0xffff0000, v79
	v_pk_add_f32 v[208:209], v[208:209], v[216:217]
	v_pk_add_f32 v[210:211], v[210:211], v[218:219]
	v_pk_add_f32 v[212:213], v[212:213], v[220:221]
	v_pk_add_f32 v[214:215], v[214:215], v[222:223]
	s_waitcnt vmcnt(20)
	v_lshlrev_b32_e32 v216, 16, v84
	v_and_b32_e32 v217, 0xffff0000, v84
	v_lshlrev_b32_e32 v218, 16, v85
	v_and_b32_e32 v219, 0xffff0000, v85
	v_lshlrev_b32_e32 v220, 16, v86
	v_and_b32_e32 v221, 0xffff0000, v86
	v_lshlrev_b32_e32 v222, 16, v87
	v_and_b32_e32 v223, 0xffff0000, v87
	v_pk_add_f32 v[208:209], v[208:209], v[216:217]
	v_pk_add_f32 v[210:211], v[210:211], v[218:219]
	v_pk_add_f32 v[212:213], v[212:213], v[220:221]
	v_pk_add_f32 v[214:215], v[214:215], v[222:223]
	s_waitcnt vmcnt(19)
	v_lshlrev_b32_e32 v216, 16, v88
	v_and_b32_e32 v217, 0xffff0000, v88
	v_lshlrev_b32_e32 v218, 16, v89
	v_and_b32_e32 v219, 0xffff0000, v89
	v_lshlrev_b32_e32 v220, 16, v90
	v_and_b32_e32 v221, 0xffff0000, v90
	v_lshlrev_b32_e32 v222, 16, v91
	v_and_b32_e32 v223, 0xffff0000, v91
	v_pk_add_f32 v[208:209], v[208:209], v[216:217]
	v_pk_add_f32 v[210:211], v[210:211], v[218:219]
	v_pk_add_f32 v[212:213], v[212:213], v[220:221]
	v_pk_add_f32 v[214:215], v[214:215], v[222:223]
	s_waitcnt vmcnt(18)
; DI unsigned pk2(float lo, float hi) { f32x2 v = {lo, hi}; bf16x2_t b = __builtin_convertvector(v, bf16x2_t); return __builtin_bit_cast(unsigned, b); }
; DI float bflo(unsigned u) { return __uint_as_float(u << 16); }
; DI float bfhi(unsigned u) { return __uint_as_float(u & 0xffff0000u); }
; DI void pool_item(const bf16_t* P, bf16_t* pooled, int idx) {
;     ...
;     for (int k = 1; k < w; ++k) if (t0 - k >= 0) { const u32x4 x = *(const u32x4*)(src + (row0 - k) * DIN);
;         sum[0] += bflo(x.x); sum[1] += bfhi(x.x); sum[2] += bflo(x.y); sum[3] += bfhi(x.y); sum[4] += bflo(x.z); sum[5] += bfhi(x.z); sum[6] += bflo(x.w); sum[7] += bfhi(x.w); }
; #pragma unroll
;     for (int j = 0; j < 8; ++j) {
;         const int t = t0 + j; const u32x4 x = *(const u32x4*)(src + (row0 + j) * DIN);
;         const float cur[8] = {bflo(x.x), bfhi(x.x), bflo(x.y), bfhi(x.y), bflo(x.z), bfhi(x.z), bflo(x.w), bfhi(x.w)};
; #pragma unroll
;         for (int e = 0; e < 8; ++e) sum[e] += cur[e];
;         const float ic = __builtin_amdgcn_rcpf((float)(t + 1 < w ? t + 1 : w));
;         u32x4 o; o.x = pk2(sum[0] * ic - cur[0], sum[1] * ic - cur[1]); o.y = pk2(sum[2] * ic - cur[2], sum[3] * ic - cur[3]);
;         o.z = pk2(sum[4] * ic - cur[4], sum[5] * ic - cur[5]); o.w = pk2(sum[6] * ic - cur[6], sum[7] * ic - cur[7]);
;         *(u32x4*)(pooled + (row0 + j) * D + ch) = o;
;         if (t - w + 1 >= 0) { const u32x4 y = *(const u32x4*)(src + (row0 + j - w + 1) * DIN);
;             sum[0] -= bflo(y.x); sum[1] -= bfhi(y.x); sum[2] -= bflo(y.y); sum[3] -= bfhi(y.y); sum[4] -= bflo(y.z); sum[5] -= bfhi(y.z); sum[6] -= bflo(y.w); sum[7] -= bfhi(y.w); }
	v_lshlrev_b32_e32 v216, 16, v92
	v_and_b32_e32 v217, 0xffff0000, v92
	v_lshlrev_b32_e32 v218, 16, v93
	v_and_b32_e32 v219, 0xffff0000, v93
	v_lshlrev_b32_e32 v220, 16, v94
	v_and_b32_e32 v221, 0xffff0000, v94
	v_lshlrev_b32_e32 v222, 16, v95
	v_and_b32_e32 v223, 0xffff0000, v95
	v_pk_add_f32 v[208:209], v[208:209], v[216:217]
	v_pk_add_f32 v[210:211], v[210:211], v[218:219]
	v_pk_add_f32 v[212:213], v[212:213], v[220:221]
	v_pk_add_f32 v[214:215], v[214:215], v[222:223]
	s_waitcnt vmcnt(17)
	v_lshlrev_b32_e32 v216, 16, v96
	v_and_b32_e32 v217, 0xffff0000, v96
	v_lshlrev_b32_e32 v218, 16, v97
	v_and_b32_e32 v219, 0xffff0000, v97
	v_lshlrev_b32_e32 v220, 16, v98
	v_and_b32_e32 v221, 0xffff0000, v98
	v_lshlrev_b32_e32 v222, 16, v99
	v_and_b32_e32 v223, 0xffff0000, v99
	v_pk_add_f32 v[208:209], v[208:209], v[216:217]
	v_pk_add_f32 v[210:211], v[210:211], v[218:219]
	v_pk_add_f32 v[212:213], v[212:213], v[220:221]
	v_pk_add_f32 v[214:215], v[214:215], v[222:223]
	s_waitcnt vmcnt(16)
	v_lshlrev_b32_e32 v216, 16, v100
	v_and_b32_e32 v217, 0xffff0000, v100
	v_lshlrev_b32_e32 v218, 16, v101
	v_and_b32_e32 v219, 0xffff0000, v101
	v_lshlrev_b32_e32 v220, 16, v102
	v_and_b32_e32 v221, 0xffff0000, v102
	v_lshlrev_b32_e32 v222, 16, v103
	v_and_b32_e32 v223, 0xffff0000, v103
	v_pk_add_f32 v[208:209], v[208:209], v[216:217]
	v_pk_add_f32 v[210:211], v[210:211], v[218:219]
	v_pk_add_f32 v[212:213], v[212:213], v[220:221]
	v_pk_add_f32 v[214:215], v[214:215], v[222:223]
	s_waitcnt vmcnt(15)
	v_lshlrev_b32_e32 v216, 16, v104
	v_and_b32_e32 v217, 0xffff0000, v104
	v_lshlrev_b32_e32 v218, 16, v105
	v_and_b32_e32 v219, 0xffff0000, v105
	v_lshlrev_b32_e32 v220, 16, v106
	v_and_b32_e32 v221, 0xffff0000, v106
	v_lshlrev_b32_e32 v222, 16, v107
	v_and_b32_e32 v223, 0xffff0000, v107
	v_pk_add_f32 v[208:209], v[208:209], v[216:217]
	v_pk_add_f32 v[210:211], v[210:211], v[218:219]
	v_pk_add_f32 v[212:213], v[212:213], v[220:221]
	v_pk_add_f32 v[214:215], v[214:215], v[222:223]
	s_mov_b64 exec, s[0:1]
.Lpool_rows:
	s_waitcnt vmcnt(14)
	v_lshlrev_b32_e32 v216, 16, v108
	v_and_b32_e32 v217, 0xffff0000, v108
	v_lshlrev_b32_e32 v218, 16, v109
	v_and_b32_e32 v219, 0xffff0000, v109
	v_lshlrev_b32_e32 v220, 16, v110
	v_and_b32_e32 v221, 0xffff0000, v110
	v_lshlrev_b32_e32 v222, 16, v111
	v_and_b32_e32 v223, 0xffff0000, v111
	v_pk_add_f32 v[208:209], v[208:209], v[216:217]
	v_pk_add_f32 v[210:211], v[210:211], v[218:219]
	v_pk_add_f32 v[212:213], v[212:213], v[220:221]
	v_pk_add_f32 v[214:215], v[214:215], v[222:223]
	v_pk_fma_f32 v[224:225], v[42:43], v[208:209], v[216:217] op_sel_hi:[0,1,1] neg_lo:[0,0,1] neg_hi:[0,0,1]
	v_pk_fma_f32 v[226:227], v[42:43], v[210:211], v[218:219] op_sel_hi:[0,1,1] neg_lo:[0,0,1] neg_hi:[0,0,1]
	v_pk_fma_f32 v[228:229], v[42:43], v[212:213], v[220:221] op_sel_hi:[0,1,1] neg_lo:[0,0,1] neg_hi:[0,0,1]
	v_pk_fma_f32 v[230:231], v[42:43], v[214:215], v[222:223] op_sel_hi:[0,1,1] neg_lo:[0,0,1] neg_hi:[0,0,1]
	v_cvt_pk_bf16_f32 v28, v224, v225
	v_cvt_pk_bf16_f32 v29, v226, v227
	v_cvt_pk_bf16_f32 v30, v228, v229
	v_cvt_pk_bf16_f32 v31, v230, v231
	global_store_dwordx4 v41, v[28:31], s[40:41]
	v_add_u32_e32 v41, 0x800, v41
	s_waitcnt vmcnt(14)
	v_lshlrev_b32_e32 v216, 16, v176
	v_and_b32_e32 v217, 0xffff0000, v176
	v_lshlrev_b32_e32 v218, 16, v177
	v_and_b32_e32 v219, 0xffff0000, v177
	v_lshlrev_b32_e32 v220, 16, v178
	v_and_b32_e32 v221, 0xffff0000, v178
	v_lshlrev_b32_e32 v222, 16, v179
	v_and_b32_e32 v223, 0xffff0000, v179
	v_pk_add_f32 v[208:209], v[208:209], v[216:217] neg_lo:[0,1] neg_hi:[0,1]
	v_pk_add_f32 v[210:211], v[210:211], v[218:219] neg_lo:[0,1] neg_hi:[0,1]
	v_pk_add_f32 v[212:213], v[212:213], v[220:221] neg_lo:[0,1] neg_hi:[0,1]
	v_pk_add_f32 v[214:215], v[214:215], v[222:223] neg_lo:[0,1] neg_hi:[0,1]
	s_waitcnt vmcnt(13)
	v_lshlrev_b32_e32 v216, 16, v112
	v_and_b32_e32 v217, 0xffff0000, v112
	v_lshlrev_b32_e32 v218, 16, v113
	v_and_b32_e32 v219, 0xffff0000, v113
	v_lshlrev_b32_e32 v220, 16, v114
	v_and_b32_e32 v221, 0xffff0000, v114
	v_lshlrev_b32_e32 v222, 16, v115
	v_and_b32_e32 v223, 0xffff0000, v115
	v_pk_add_f32 v[208:209], v[208:209], v[216:217]
	v_pk_add_f32 v[210:211], v[210:211], v[218:219]
	v_pk_add_f32 v[212:213], v[212:213], v[220:221]
	v_pk_add_f32 v[214:215], v[214:215], v[222:223]
	v_pk_fma_f32 v[224:225], v[42:43], v[208:209], v[216:217] op_sel_hi:[0,1,1] neg_lo:[0,0,1] neg_hi:[0,0,1]
	v_pk_fma_f32 v[226:227], v[42:43], v[210:211], v[218:219] op_sel_hi:[0,1,1] neg_lo:[0,0,1] neg_hi:[0,0,1]
	v_pk_fma_f32 v[228:229], v[42:43], v[212:213], v[220:221] op_sel_hi:[0,1,1] neg_lo:[0,0,1] neg_hi:[0,0,1]
	v_pk_fma_f32 v[230:231], v[42:43], v[214:215], v[222:223] op_sel_hi:[0,1,1] neg_lo:[0,0,1] neg_hi:[0,0,1]
	v_cvt_pk_bf16_f32 v28, v224, v225
	v_cvt_pk_bf16_f32 v29, v226, v227
	v_cvt_pk_bf16_f32 v30, v228, v229
	v_cvt_pk_bf16_f32 v31, v230, v231
	global_store_dwordx4 v41, v[28:31], s[40:41]
	v_add_u32_e32 v41, 0x800, v41
	s_waitcnt vmcnt(13)
	v_lshlrev_b32_e32 v216, 16, v180
	v_and_b32_e32 v217, 0xffff0000, v180
	v_lshlrev_b32_e32 v218, 16, v181
	v_and_b32_e32 v219, 0xffff0000, v181
	v_lshlrev_b32_e32 v220, 16, v182
	v_and_b32_e32 v221, 0xffff0000, v182
	v_lshlrev_b32_e32 v222, 16, v183
	v_and_b32_e32 v223, 0xffff0000, v183
	v_pk_add_f32 v[208:209], v[208:209], v[216:217] neg_lo:[0,1] neg_hi:[0,1]
	v_pk_add_f32 v[210:211], v[210:211], v[218:219] neg_lo:[0,1] neg_hi:[0,1]
	v_pk_add_f32 v[212:213], v[212:213], v[220:221] neg_lo:[0,1] neg_hi:[0,1]
	v_pk_add_f32 v[214:215], v[214:215], v[222:223] neg_lo:[0,1] neg_hi:[0,1]
	s_waitcnt vmcnt(12)
; DI unsigned pk2(float lo, float hi) { f32x2 v = {lo, hi}; bf16x2_t b = __builtin_convertvector(v, bf16x2_t); return __builtin_bit_cast(unsigned, b); }
; DI float bflo(unsigned u) { return __uint_as_float(u << 16); }
; DI float bfhi(unsigned u) { return __uint_as_float(u & 0xffff0000u); }
; DI void pool_item(const bf16_t* P, bf16_t* pooled, int idx) {
;     ...
;     for (int j = 0; j < 8; ++j) {
;         const int t = t0 + j; const u32x4 x = *(const u32x4*)(src + (row0 + j) * DIN);
;         const float cur[8] = {bflo(x.x), bfhi(x.x), bflo(x.y), bfhi(x.y), bflo(x.z), bfhi(x.z), bflo(x.w), bfhi(x.w)};
; #pragma unroll
;         for (int e = 0; e < 8; ++e) sum[e] += cur[e];
;         const float ic = __builtin_amdgcn_rcpf((float)(t + 1 < w ? t + 1 : w));
;         u32x4 o; o.x = pk2(sum[0] * ic - cur[0], sum[1] * ic - cur[1]); o.y = pk2(sum[2] * ic - cur[2], sum[3] * ic - cur[3]);
;         o.z = pk2(sum[4] * ic - cur[4], sum[5] * ic - cur[5]); o.w = pk2(sum[6] * ic - cur[6], sum[7] * ic - cur[7]);
;         *(u32x4*)(pooled + (row0 + j) * D + ch) = o;
;         if (t - w + 1 >= 0) { const u32x4 y = *(const u32x4*)(src + (row0 + j - w + 1) * DIN);
;             sum[0] -= bflo(y.x); sum[1] -= bfhi(y.x); sum[2] -= bflo(y.y); sum[3] -= bfhi(y.y); sum[4] -= bflo(y.z); sum[5] -= bfhi(y.z); sum[6] -= bflo(y.w); sum[7] -= bfhi(y.w); }
	v_lshlrev_b32_e32 v216, 16, v116
	v_and_b32_e32 v217, 0xffff0000, v116
	v_lshlrev_b32_e32 v218, 16, v117
	v_and_b32_e32 v219, 0xffff0000, v117
	v_lshlrev_b32_e32 v220, 16, v118
	v_and_b32_e32 v221, 0xffff0000, v118
	v_lshlrev_b32_e32 v222, 16, v119
	v_and_b32_e32 v223, 0xffff0000, v119
	v_pk_add_f32 v[208:209], v[208:209], v[216:217]
	v_pk_add_f32 v[210:211], v[210:211], v[218:219]
	v_pk_add_f32 v[212:213], v[212:213], v[220:221]
	v_pk_add_f32 v[214:215], v[214:215], v[222:223]
	v_pk_fma_f32 v[224:225], v[42:43], v[208:209], v[216:217] op_sel_hi:[0,1,1] neg_lo:[0,0,1] neg_hi:[0,0,1]
	v_pk_fma_f32 v[226:227], v[42:43], v[210:211], v[218:219] op_sel_hi:[0,1,1] neg_lo:[0,0,1] neg_hi:[0,0,1]
	v_pk_fma_f32 v[228:229], v[42:43], v[212:213], v[220:221] op_sel_hi:[0,1,1] neg_lo:[0,0,1] neg_hi:[0,0,1]
	v_pk_fma_f32 v[230:231], v[42:43], v[214:215], v[222:223] op_sel_hi:[0,1,1] neg_lo:[0,0,1] neg_hi:[0,0,1]
	v_cvt_pk_bf16_f32 v28, v224, v225
	v_cvt_pk_bf16_f32 v29, v226, v227
	v_cvt_pk_bf16_f32 v30, v228, v229
	v_cvt_pk_bf16_f32 v31, v230, v231
	global_store_dwordx4 v41, v[28:31], s[40:41]
	v_add_u32_e32 v41, 0x800, v41
	s_waitcnt vmcnt(12)
	v_lshlrev_b32_e32 v216, 16, v184
	v_and_b32_e32 v217, 0xffff0000, v184
	v_lshlrev_b32_e32 v218, 16, v185
	v_and_b32_e32 v219, 0xffff0000, v185
	v_lshlrev_b32_e32 v220, 16, v186
	v_and_b32_e32 v221, 0xffff0000, v186
	v_lshlrev_b32_e32 v222, 16, v187
	v_and_b32_e32 v223, 0xffff0000, v187
	v_pk_add_f32 v[208:209], v[208:209], v[216:217] neg_lo:[0,1] neg_hi:[0,1]
	v_pk_add_f32 v[210:211], v[210:211], v[218:219] neg_lo:[0,1] neg_hi:[0,1]
	v_pk_add_f32 v[212:213], v[212:213], v[220:221] neg_lo:[0,1] neg_hi:[0,1]
	v_pk_add_f32 v[214:215], v[214:215], v[222:223] neg_lo:[0,1] neg_hi:[0,1]
	s_waitcnt vmcnt(11)
	v_lshlrev_b32_e32 v216, 16, v120
	v_and_b32_e32 v217, 0xffff0000, v120
	v_lshlrev_b32_e32 v218, 16, v121
	v_and_b32_e32 v219, 0xffff0000, v121
	v_lshlrev_b32_e32 v220, 16, v122
	v_and_b32_e32 v221, 0xffff0000, v122
	v_lshlrev_b32_e32 v222, 16, v123
	v_and_b32_e32 v223, 0xffff0000, v123
	v_pk_add_f32 v[208:209], v[208:209], v[216:217]
	v_pk_add_f32 v[210:211], v[210:211], v[218:219]
	v_pk_add_f32 v[212:213], v[212:213], v[220:221]
	v_pk_add_f32 v[214:215], v[214:215], v[222:223]
	v_pk_fma_f32 v[224:225], v[42:43], v[208:209], v[216:217] op_sel_hi:[0,1,1] neg_lo:[0,0,1] neg_hi:[0,0,1]
	v_pk_fma_f32 v[226:227], v[42:43], v[210:211], v[218:219] op_sel_hi:[0,1,1] neg_lo:[0,0,1] neg_hi:[0,0,1]
	v_pk_fma_f32 v[228:229], v[42:43], v[212:213], v[220:221] op_sel_hi:[0,1,1] neg_lo:[0,0,1] neg_hi:[0,0,1]
	v_pk_fma_f32 v[230:231], v[42:43], v[214:215], v[222:223] op_sel_hi:[0,1,1] neg_lo:[0,0,1] neg_hi:[0,0,1]
	v_cvt_pk_bf16_f32 v28, v224, v225
	v_cvt_pk_bf16_f32 v29, v226, v227
	v_cvt_pk_bf16_f32 v30, v228, v229
	v_cvt_pk_bf16_f32 v31, v230, v231
	global_store_dwordx4 v41, v[28:31], s[40:41]
	v_add_u32_e32 v41, 0x800, v41
	s_waitcnt vmcnt(11)
	v_lshlrev_b32_e32 v216, 16, v188
	v_and_b32_e32 v217, 0xffff0000, v188
	v_lshlrev_b32_e32 v218, 16, v189
	v_and_b32_e32 v219, 0xffff0000, v189
	v_lshlrev_b32_e32 v220, 16, v190
	v_and_b32_e32 v221, 0xffff0000, v190
	v_lshlrev_b32_e32 v222, 16, v191
	v_and_b32_e32 v223, 0xffff0000, v191
	v_pk_add_f32 v[208:209], v[208:209], v[216:217] neg_lo:[0,1] neg_hi:[0,1]
	v_pk_add_f32 v[210:211], v[210:211], v[218:219] neg_lo:[0,1] neg_hi:[0,1]
	v_pk_add_f32 v[212:213], v[212:213], v[220:221] neg_lo:[0,1] neg_hi:[0,1]
	v_pk_add_f32 v[214:215], v[214:215], v[222:223] neg_lo:[0,1] neg_hi:[0,1]
	s_waitcnt vmcnt(10)
	v_lshlrev_b32_e32 v216, 16, v124
	v_and_b32_e32 v217, 0xffff0000, v124
	v_lshlrev_b32_e32 v218, 16, v125
	v_and_b32_e32 v219, 0xffff0000, v125
	v_lshlrev_b32_e32 v220, 16, v126
	v_and_b32_e32 v221, 0xffff0000, v126
	v_lshlrev_b32_e32 v222, 16, v127
	v_and_b32_e32 v223, 0xffff0000, v127
	v_pk_add_f32 v[208:209], v[208:209], v[216:217]
	v_pk_add_f32 v[210:211], v[210:211], v[218:219]
	v_pk_add_f32 v[212:213], v[212:213], v[220:221]
	v_pk_add_f32 v[214:215], v[214:215], v[222:223]
	v_pk_fma_f32 v[224:225], v[42:43], v[208:209], v[216:217] op_sel_hi:[0,1,1] neg_lo:[0,0,1] neg_hi:[0,0,1]
	v_pk_fma_f32 v[226:227], v[42:43], v[210:211], v[218:219] op_sel_hi:[0,1,1] neg_lo:[0,0,1] neg_hi:[0,0,1]
	v_pk_fma_f32 v[228:229], v[42:43], v[212:213], v[220:221] op_sel_hi:[0,1,1] neg_lo:[0,0,1] neg_hi:[0,0,1]
	v_pk_fma_f32 v[230:231], v[42:43], v[214:215], v[222:223] op_sel_hi:[0,1,1] neg_lo:[0,0,1] neg_hi:[0,0,1]
	v_cvt_pk_bf16_f32 v28, v224, v225
	v_cvt_pk_bf16_f32 v29, v226, v227
	v_cvt_pk_bf16_f32 v30, v228, v229
	v_cvt_pk_bf16_f32 v31, v230, v231
	global_store_dwordx4 v41, v[28:31], s[40:41]
	v_add_u32_e32 v41, 0x800, v41
	s_waitcnt vmcnt(10)
	v_lshlrev_b32_e32 v216, 16, v192
	v_and_b32_e32 v217, 0xffff0000, v192
	v_lshlrev_b32_e32 v218, 16, v193
	v_and_b32_e32 v219, 0xffff0000, v193
	v_lshlrev_b32_e32 v220, 16, v194
	v_and_b32_e32 v221, 0xffff0000, v194
	v_lshlrev_b32_e32 v222, 16, v195
	v_and_b32_e32 v223, 0xffff0000, v195
	v_pk_add_f32 v[208:209], v[208:209], v[216:217] neg_lo:[0,1] neg_hi:[0,1]
	v_pk_add_f32 v[210:211], v[210:211], v[218:219] neg_lo:[0,1] neg_hi:[0,1]
	v_pk_add_f32 v[212:213], v[212:213], v[220:221] neg_lo:[0,1] neg_hi:[0,1]
	v_pk_add_f32 v[214:215], v[214:215], v[222:223] neg_lo:[0,1] neg_hi:[0,1]
	s_waitcnt vmcnt(9)
; DI unsigned pk2(float lo, float hi) { f32x2 v = {lo, hi}; bf16x2_t b = __builtin_convertvector(v, bf16x2_t); return __builtin_bit_cast(unsigned, b); }
; DI float bflo(unsigned u) { return __uint_as_float(u << 16); }
; DI float bfhi(unsigned u) { return __uint_as_float(u & 0xffff0000u); }
; DI void pool_item(const bf16_t* P, bf16_t* pooled, int idx) {
;     ...
;     for (int j = 0; j < 8; ++j) {
;         const int t = t0 + j; const u32x4 x = *(const u32x4*)(src + (row0 + j) * DIN);
;         const float cur[8] = {bflo(x.x), bfhi(x.x), bflo(x.y), bfhi(x.y), bflo(x.z), bfhi(x.z), bflo(x.w), bfhi(x.w)};
; #pragma unroll
;         for (int e = 0; e < 8; ++e) sum[e] += cur[e];
;         const float ic = __builtin_amdgcn_rcpf((float)(t + 1 < w ? t + 1 : w));
;         u32x4 o; o.x = pk2(sum[0] * ic - cur[0], sum[1] * ic - cur[1]); o.y = pk2(sum[2] * ic - cur[2], sum[3] * ic - cur[3]);
;         o.z = pk2(sum[4] * ic - cur[4], sum[5] * ic - cur[5]); o.w = pk2(sum[6] * ic - cur[6], sum[7] * ic - cur[7]);
;         *(u32x4*)(pooled + (row0 + j) * D + ch) = o;
;         if (t - w + 1 >= 0) { const u32x4 y = *(const u32x4*)(src + (row0 + j - w + 1) * DIN);
;             sum[0] -= bflo(y.x); sum[1] -= bfhi(y.x); sum[2] -= bflo(y.y); sum[3] -= bfhi(y.y); sum[4] -= bflo(y.z); sum[5] -= bfhi(y.z); sum[6] -= bflo(y.w); sum[7] -= bfhi(y.w); }
; __global__ void __launch_bounds__(512, 2) mega_fwd(Params p) {
;     ...
;                     for (int idx = bx * 512 + tid; idx < (MC / 8) * 128; idx += G * 512) pool_item(proj, (bf16_t*)(ws + WS_POOLED), idx);
	v_lshlrev_b32_e32 v216, 16, v128
	v_and_b32_e32 v217, 0xffff0000, v128
	v_lshlrev_b32_e32 v218, 16, v129
	v_and_b32_e32 v219, 0xffff0000, v129
	v_lshlrev_b32_e32 v220, 16, v130
	v_and_b32_e32 v221, 0xffff0000, v130
	v_lshlrev_b32_e32 v222, 16, v131
	v_and_b32_e32 v223, 0xffff0000, v131
	v_pk_add_f32 v[208:209], v[208:209], v[216:217]
	v_pk_add_f32 v[210:211], v[210:211], v[218:219]
	v_pk_add_f32 v[212:213], v[212:213], v[220:221]
	v_pk_add_f32 v[214:215], v[214:215], v[222:223]
	v_pk_fma_f32 v[224:225], v[42:43], v[208:209], v[216:217] op_sel_hi:[0,1,1] neg_lo:[0,0,1] neg_hi:[0,0,1]
	v_pk_fma_f32 v[226:227], v[42:43], v[210:211], v[218:219] op_sel_hi:[0,1,1] neg_lo:[0,0,1] neg_hi:[0,0,1]
	v_pk_fma_f32 v[228:229], v[42:43], v[212:213], v[220:221] op_sel_hi:[0,1,1] neg_lo:[0,0,1] neg_hi:[0,0,1]
	v_pk_fma_f32 v[230:231], v[42:43], v[214:215], v[222:223] op_sel_hi:[0,1,1] neg_lo:[0,0,1] neg_hi:[0,0,1]
	v_cvt_pk_bf16_f32 v28, v224, v225
	v_cvt_pk_bf16_f32 v29, v226, v227
	v_cvt_pk_bf16_f32 v30, v228, v229
	v_cvt_pk_bf16_f32 v31, v230, v231
	global_store_dwordx4 v41, v[28:31], s[40:41]
	v_add_u32_e32 v41, 0x800, v41
	s_waitcnt vmcnt(9)
	v_lshlrev_b32_e32 v216, 16, v196
	v_and_b32_e32 v217, 0xffff0000, v196
	v_lshlrev_b32_e32 v218, 16, v197
	v_and_b32_e32 v219, 0xffff0000, v197
	v_lshlrev_b32_e32 v220, 16, v198
	v_and_b32_e32 v221, 0xffff0000, v198
	v_lshlrev_b32_e32 v222, 16, v199
	v_and_b32_e32 v223, 0xffff0000, v199
	v_pk_add_f32 v[208:209], v[208:209], v[216:217] neg_lo:[0,1] neg_hi:[0,1]
	v_pk_add_f32 v[210:211], v[210:211], v[218:219] neg_lo:[0,1] neg_hi:[0,1]
	v_pk_add_f32 v[212:213], v[212:213], v[220:221] neg_lo:[0,1] neg_hi:[0,1]
	v_pk_add_f32 v[214:215], v[214:215], v[222:223] neg_lo:[0,1] neg_hi:[0,1]
	s_waitcnt vmcnt(8)
	v_lshlrev_b32_e32 v216, 16, v132
	v_and_b32_e32 v217, 0xffff0000, v132
	v_lshlrev_b32_e32 v218, 16, v133
	v_and_b32_e32 v219, 0xffff0000, v133
	v_lshlrev_b32_e32 v220, 16, v134
	v_and_b32_e32 v221, 0xffff0000, v134
	v_lshlrev_b32_e32 v222, 16, v135
	v_and_b32_e32 v223, 0xffff0000, v135
	v_pk_add_f32 v[208:209], v[208:209], v[216:217]
	v_pk_add_f32 v[210:211], v[210:211], v[218:219]
	v_pk_add_f32 v[212:213], v[212:213], v[220:221]
	v_pk_add_f32 v[214:215], v[214:215], v[222:223]
	v_pk_fma_f32 v[224:225], v[42:43], v[208:209], v[216:217] op_sel_hi:[0,1,1] neg_lo:[0,0,1] neg_hi:[0,0,1]
	v_pk_fma_f32 v[226:227], v[42:43], v[210:211], v[218:219] op_sel_hi:[0,1,1] neg_lo:[0,0,1] neg_hi:[0,0,1]
	v_pk_fma_f32 v[228:229], v[42:43], v[212:213], v[220:221] op_sel_hi:[0,1,1] neg_lo:[0,0,1] neg_hi:[0,0,1]
	v_pk_fma_f32 v[230:231], v[42:43], v[214:215], v[222:223] op_sel_hi:[0,1,1] neg_lo:[0,0,1] neg_hi:[0,0,1]
	v_cvt_pk_bf16_f32 v28, v224, v225
	v_cvt_pk_bf16_f32 v29, v226, v227
	v_cvt_pk_bf16_f32 v30, v228, v229
	v_cvt_pk_bf16_f32 v31, v230, v231
	global_store_dwordx4 v41, v[28:31], s[40:41]
	v_add_u32_e32 v41, 0x800, v41
	s_waitcnt vmcnt(8)
	v_lshlrev_b32_e32 v216, 16, v200
	v_and_b32_e32 v217, 0xffff0000, v200
	v_lshlrev_b32_e32 v218, 16, v201
	v_and_b32_e32 v219, 0xffff0000, v201
	v_lshlrev_b32_e32 v220, 16, v202
	v_and_b32_e32 v221, 0xffff0000, v202
	v_lshlrev_b32_e32 v222, 16, v203
	v_and_b32_e32 v223, 0xffff0000, v203
	v_pk_add_f32 v[208:209], v[208:209], v[216:217] neg_lo:[0,1] neg_hi:[0,1]
	v_pk_add_f32 v[210:211], v[210:211], v[218:219] neg_lo:[0,1] neg_hi:[0,1]
	v_pk_add_f32 v[212:213], v[212:213], v[220:221] neg_lo:[0,1] neg_hi:[0,1]
	v_pk_add_f32 v[214:215], v[214:215], v[222:223] neg_lo:[0,1] neg_hi:[0,1]
	s_waitcnt vmcnt(7)
	v_lshlrev_b32_e32 v216, 16, v136
	v_and_b32_e32 v217, 0xffff0000, v136
	v_lshlrev_b32_e32 v218, 16, v137
	v_and_b32_e32 v219, 0xffff0000, v137
	v_lshlrev_b32_e32 v220, 16, v138
	v_and_b32_e32 v221, 0xffff0000, v138
	v_lshlrev_b32_e32 v222, 16, v139
	v_and_b32_e32 v223, 0xffff0000, v139
	v_pk_add_f32 v[208:209], v[208:209], v[216:217]
	v_pk_add_f32 v[210:211], v[210:211], v[218:219]
	v_pk_add_f32 v[212:213], v[212:213], v[220:221]
	v_pk_add_f32 v[214:215], v[214:215], v[222:223]
	v_pk_fma_f32 v[224:225], v[42:43], v[208:209], v[216:217] op_sel_hi:[0,1,1] neg_lo:[0,0,1] neg_hi:[0,0,1]
	v_pk_fma_f32 v[226:227], v[42:43], v[210:211], v[218:219] op_sel_hi:[0,1,1] neg_lo:[0,0,1] neg_hi:[0,0,1]
	v_pk_fma_f32 v[228:229], v[42:43], v[212:213], v[220:221] op_sel_hi:[0,1,1] neg_lo:[0,0,1] neg_hi:[0,0,1]
	v_pk_fma_f32 v[230:231], v[42:43], v[214:215], v[222:223] op_sel_hi:[0,1,1] neg_lo:[0,0,1] neg_hi:[0,0,1]
	v_cvt_pk_bf16_f32 v28, v224, v225
	v_cvt_pk_bf16_f32 v29, v226, v227
	v_cvt_pk_bf16_f32 v30, v228, v229
	v_cvt_pk_bf16_f32 v31, v230, v231
	global_store_dwordx4 v41, v[28:31], s[40:41]
	v_add_u32_e32 v22, s87, v22
	s_mov_b32 s0, 0x3ffff
	v_cmp_lt_i32_e32 vcc, s0, v22
	v_add_u32_e32 v23, s13, v23
	s_or_b64 s[46:47], vcc, s[46:47]
	s_andn2_b64 exec, exec, s[46:47]
	s_cbranch_execz .LBB0_328
	s_branch .LBB0_310

; DI void rnn_phase(LAS unsigned char* lds, bf16_t* P, const bf16_t* WaT, const bf16_t* WiT, const float* convw, const float* convb, const float* ba, const float* bi, const float* lam,
;                   f32x2* sums, unsigned* au, bool fin, int bx, int G, int tid, int wid, int lane) {
;     ...
;             const int hbk = u2 & 15, c = (u2 >> 4) & 63, b = u2 >> 10;
;             const size_t rowbase = (size_t)b * SEQ + c * 128; const int ch0 = hbk * 64, ch = lane, seg = wid;
;             const unsigned* aup = au + (rowbase + 16 * seg) * D + ch0 + ch;
;             bf16_t* yp = P + (rowbase + 16 * seg) * DIN + PC_Y + ch0 + ch;
;             unsigned w[16]; unsigned short yv[16];
; #pragma unroll
;             for (int j = 0; j < 16; ++j) { w[j] = aup[(size_t)j * D]; yv[j] = yp[(size_t)j * DIN]; }
;             float Ap = 1.f, Hp = 0.f;
; #pragma unroll
;             for (int k = 0; k < 8; ++k) { const int j = 8 * wid + k; if (j < c) { const f32x2 sv = sums[((size_t)b * NCH + j) * D + ch0 + lane]; Hp = sv.x * Hp + sv.y; Ap *= sv.x; } }
.LBB0_369:
	s_ashr_i32 s38, s1, 10
	s_bfe_u32 s21, s1, 0x60004
	s_ashr_i32 s39, s38, 31
	s_lshl_b32 s22, s1, 6
	s_lshl_b64 s[72:73], s[38:39], 13
	s_lshl_b32 s23, s21, 7
	s_and_b32 s22, s22, 0x3c0
	s_add_u32 s25, s72, s12
	s_addc_u32 s41, s73, s18
	s_add_u32 s72, s25, s23
	s_addc_u32 s73, s41, 0
	s_lshl_b64 s[74:75], s[72:73], 12
	s_add_u32 s23, s44, s74
	s_addc_u32 s25, s45, s75
	s_lshl_b32 s41, s22, 2
	s_add_u32 s74, s23, s41
	s_addc_u32 s75, s25, 0
	s_mul_i32 s23, s73, 0x3c00
	s_mul_hi_u32 s25, s72, 0x3c00
	s_add_i32 s25, s25, s23
	s_mul_i32 s23, s72, 0x3c00
	s_add_u32 s23, s42, s23
	v_lshlrev_b32_e32 v80, 2, v64
	s_addc_u32 s25, s43, s25
	s_lshl_b32 s41, s22, 1
	v_lshl_add_u64 v[2:3], s[74:75], 0, v[80:81]
	s_add_u32 s72, s23, s41
	s_addc_u32 s73, s25, 0
	v_lshlrev_b32_e32 v80, 1, v64
	v_add_co_u32_e32 v4, vcc, s15, v2
	v_lshl_add_u64 v[0:1], s[72:73], 0, v[80:81]
	s_nop 0
	v_addc_co_u32_e32 v5, vcc, 0, v3, vcc
	s_movk_i32 s25, 0x4000
	flat_load_dword v53, v[2:3]
	flat_load_ushort v58, v[0:1] offset:2048
	flat_load_dword v56, v[4:5]
	v_add_co_u32_e32 v4, vcc, s25, v0
	s_movk_i32 s23, 0x2000
	s_nop 0
	v_addc_co_u32_e32 v5, vcc, 0, v1, vcc
	flat_load_ushort v55, v[4:5] offset:1024
	v_add_co_u32_e32 v4, vcc, s23, v2
	s_mov_b32 s41, 0x8000
	s_nop 0
	v_addc_co_u32_e32 v5, vcc, 0, v3, vcc
	flat_load_dword v60, v[4:5]
	v_add_co_u32_e32 v4, vcc, s41, v0
	s_movk_i32 s23, 0x3000
	s_nop 0
	v_addc_co_u32_e32 v5, vcc, 0, v1, vcc
	flat_load_ushort v51, v[4:5]
	v_add_co_u32_e32 v4, vcc, s23, v2
	s_mov_b32 s49, 0xb000
	s_nop 0
	v_addc_co_u32_e32 v5, vcc, 0, v3, vcc
	flat_load_dword v62, v[4:5]
	v_add_co_u32_e32 v4, vcc, s49, v0
	s_movk_i32 s23, 0x5000
	s_nop 0
	v_addc_co_u32_e32 v5, vcc, 0, v1, vcc
	flat_load_ushort v49, v[4:5] offset:3072
	v_add_co_u32_e32 v4, vcc, s25, v2
	s_mov_b32 s25, 0xf000
	s_nop 0
	v_addc_co_u32_e32 v5, vcc, 0, v3, vcc
	flat_load_dword v63, v[4:5]
	v_add_co_u32_e32 v4, vcc, s25, v0
	s_lshl_b64 s[38:39], s[38:39], 19
	s_nop 0
	v_addc_co_u32_e32 v5, vcc, 0, v1, vcc
	flat_load_ushort v47, v[4:5] offset:2048
	v_add_co_u32_e32 v4, vcc, s23, v2
	s_mov_b32 s23, 0x13000
	s_nop 0
	v_addc_co_u32_e32 v5, vcc, 0, v3, vcc
	flat_load_dword v65, v[4:5]
	v_add_co_u32_e32 v4, vcc, s23, v0
	s_movk_i32 s23, 0x6000
	s_nop 0
	v_addc_co_u32_e32 v5, vcc, 0, v1, vcc
	flat_load_ushort v44, v[4:5] offset:1024
	v_add_co_u32_e32 v4, vcc, s23, v2
	s_mov_b32 s23, 0x17000
	s_nop 0
	v_addc_co_u32_e32 v5, vcc, 0, v3, vcc
	flat_load_dword v67, v[4:5]
	v_add_co_u32_e32 v4, vcc, s23, v0
	s_movk_i32 s23, 0x7000
	s_nop 0
	v_addc_co_u32_e32 v5, vcc, 0, v1, vcc
	flat_load_ushort v43, v[4:5]
	v_add_co_u32_e32 v4, vcc, s23, v2
	s_mov_b32 s23, 0x1a000
	s_nop 0
	v_addc_co_u32_e32 v5, vcc, 0, v3, vcc
	flat_load_dword v68, v[4:5]
	v_add_co_u32_e32 v4, vcc, s23, v0
	s_mov_b32 s23, 0x9000
	s_nop 0
	v_addc_co_u32_e32 v5, vcc, 0, v1, vcc
	flat_load_ushort v42, v[4:5] offset:3072
	v_add_co_u32_e32 v4, vcc, s41, v2
	v_lshlrev_b32_e32 v80, 3, v64
	s_nop 0
	v_addc_co_u32_e32 v5, vcc, 0, v3, vcc
	flat_load_dword v69, v[4:5]
	v_add_co_u32_e32 v4, vcc, s76, v0
	s_nop 1
	v_addc_co_u32_e32 v5, vcc, 0, v1, vcc
	flat_load_ushort v41, v[4:5] offset:2048
	v_add_co_u32_e32 v4, vcc, s23, v2
	s_mov_b32 s23, 0x22000
	s_nop 0
	v_addc_co_u32_e32 v5, vcc, 0, v3, vcc
	flat_load_dword v70, v[4:5]
	v_add_co_u32_e32 v4, vcc, s23, v0
	s_mov_b32 s23, 0xa000
	s_nop 0
	v_addc_co_u32_e32 v5, vcc, 0, v1, vcc
	flat_load_ushort v40, v[4:5] offset:1024
	v_add_co_u32_e32 v4, vcc, s23, v2
	s_mov_b32 s23, 0x26000
	s_nop 0
	v_addc_co_u32_e32 v5, vcc, 0, v3, vcc
	flat_load_dword v71, v[4:5]
	v_add_co_u32_e32 v4, vcc, s23, v0
	s_mov_b32 s23, 0x29000
	s_nop 0
	v_addc_co_u32_e32 v5, vcc, 0, v1, vcc
	flat_load_ushort v39, v[4:5]
	v_add_co_u32_e32 v4, vcc, s49, v2
	s_nop 1
	v_addc_co_u32_e32 v5, vcc, 0, v3, vcc
	flat_load_dword v73, v[4:5]
	v_add_co_u32_e32 v4, vcc, s23, v0
	s_mov_b32 s23, 0xc000
	s_nop 0
	v_addc_co_u32_e32 v5, vcc, 0, v1, vcc
	flat_load_ushort v38, v[4:5] offset:3072
	v_add_co_u32_e32 v4, vcc, s23, v2
	s_mov_b32 s23, 0x2d000
	s_nop 0
	v_addc_co_u32_e32 v5, vcc, 0, v3, vcc
	flat_load_dword v74, v[4:5]
	v_add_co_u32_e32 v4, vcc, s23, v0
	s_mov_b32 s23, 0xd000
	s_nop 0
	v_addc_co_u32_e32 v5, vcc, 0, v1, vcc
	flat_load_ushort v37, v[4:5] offset:2048
	v_add_co_u32_e32 v4, vcc, s23, v2
	s_mov_b32 s23, 0x31000
	s_nop 0
	v_addc_co_u32_e32 v5, vcc, 0, v3, vcc
	flat_load_dword v75, v[4:5]
	v_add_co_u32_e32 v4, vcc, s23, v0
	s_mov_b32 s23, 0xe000
	s_nop 0
	v_addc_co_u32_e32 v5, vcc, 0, v1, vcc
	flat_load_ushort v36, v[4:5] offset:1024
	v_add_co_u32_e32 v4, vcc, s23, v2
	s_mov_b32 s23, 0x35000
	s_nop 0
	v_addc_co_u32_e32 v5, vcc, 0, v3, vcc
	flat_load_dword v77, v[4:5]
	v_add_co_u32_e32 v4, vcc, s23, v0
	s_mov_b32 s23, 0x38000
	s_nop 0
	v_addc_co_u32_e32 v5, vcc, 0, v1, vcc
	v_add_co_u32_e32 v2, vcc, s25, v2
	flat_load_ushort v35, v[4:5]
	s_nop 0
	v_addc_co_u32_e32 v3, vcc, 0, v3, vcc
	flat_load_dword v78, v[2:3]
	v_add_co_u32_e32 v2, vcc, s23, v0
	s_add_u32 s23, s16, s38
	s_nop 0
	v_addc_co_u32_e32 v3, vcc, 0, v1, vcc
	flat_load_ushort v34, v[2:3] offset:3072
	s_addc_u32 s25, s17, s39
	s_lshl_b32 s22, s22, 3
	s_add_u32 s22, s23, s22
	s_addc_u32 s23, s25, 0
	v_lshl_add_u64 v[4:5], s[22:23], 0, v[80:81]
	v_lshl_add_u64 v[92:93], v[4:5], 0, s[36:37]
	v_lshl_add_u64 v[94:95], v[4:5], 0, s[46:47]
	v_lshl_add_u64 v[96:97], v[4:5], 0, s[50:51]
	v_lshl_add_u64 v[98:99], v[4:5], 0, s[54:55]
	v_lshl_add_u64 v[100:101], v[4:5], 0, s[58:59]
	v_lshl_add_u64 v[102:103], v[4:5], 0, s[62:63]
	v_lshl_add_u64 v[104:105], v[4:5], 0, s[66:67]
	v_lshl_add_u64 v[106:107], v[4:5], 0, s[70:71]
	global_load_dwordx2 v[108:109], v[92:93], off
	global_load_dwordx2 v[110:111], v[94:95], off
	global_load_dwordx2 v[112:113], v[96:97], off
	global_load_dwordx2 v[114:115], v[98:99], off
	global_load_dwordx2 v[116:117], v[100:101], off
	global_load_dwordx2 v[118:119], v[102:103], off
	global_load_dwordx2 v[120:121], v[104:105], off
	global_load_dwordx2 v[122:123], v[106:107], off
	v_mov_b32_e32 v2, 1.0
	v_mov_b32_e32 v3, 0
	s_cmp_lt_i32 s0, s21
	s_cselect_b64 vcc, -1, 0
	s_waitcnt vmcnt(7)
; DI void rnn_phase(LAS unsigned char* lds, bf16_t* P, const bf16_t* WaT, const bf16_t* WiT, const float* convw, const float* convb, const float* ba, const float* bi, const float* lam,
;                   f32x2* sums, unsigned* au, bool fin, int bx, int G, int tid, int wid, int lane) {
;     ...
;             for (int k = 0; k < 8; ++k) { const int j = 8 * wid + k; if (j < c) { const f32x2 sv = sums[((size_t)b * NCH + j) * D + ch0 + lane]; Hp = sv.x * Hp + sv.y; Ap *= sv.x; } }
	v_cndmask_b32_e32 v108, 1.0, v108, vcc
	v_cndmask_b32_e32 v109, 0, v109, vcc
	v_fmac_f32_e32 v109, v3, v108
	v_mul_f32_e32 v2, v2, v108
	v_mov_b32_e32 v3, v109
	s_cmp_lt_i32 s40, s21
	s_cselect_b64 vcc, -1, 0
	s_waitcnt vmcnt(6)
	v_cndmask_b32_e32 v110, 1.0, v110, vcc
	v_cndmask_b32_e32 v111, 0, v111, vcc
	v_fmac_f32_e32 v111, v3, v110
	v_mul_f32_e32 v2, v2, v110
	v_mov_b32_e32 v3, v111
	s_cmp_lt_i32 s48, s21
	s_cselect_b64 vcc, -1, 0
	s_waitcnt vmcnt(5)
	v_cndmask_b32_e32 v112, 1.0, v112, vcc
	v_cndmask_b32_e32 v113, 0, v113, vcc
	v_fmac_f32_e32 v113, v3, v112
	v_mul_f32_e32 v2, v2, v112
	v_mov_b32_e32 v3, v113
	s_cmp_lt_i32 s52, s21
	s_cselect_b64 vcc, -1, 0
	s_waitcnt vmcnt(4)
	v_cndmask_b32_e32 v114, 1.0, v114, vcc
	v_cndmask_b32_e32 v115, 0, v115, vcc
	v_fmac_f32_e32 v115, v3, v114
	v_mul_f32_e32 v2, v2, v114
	v_mov_b32_e32 v3, v115
	s_cmp_lt_i32 s56, s21
	s_cselect_b64 vcc, -1, 0
	s_waitcnt vmcnt(3)
	v_cndmask_b32_e32 v116, 1.0, v116, vcc
	v_cndmask_b32_e32 v117, 0, v117, vcc
	v_fmac_f32_e32 v117, v3, v116
	v_mul_f32_e32 v2, v2, v116
	v_mov_b32_e32 v3, v117
	s_cmp_lt_i32 s60, s21
	s_cselect_b64 vcc, -1, 0
	s_waitcnt vmcnt(2)
	v_cndmask_b32_e32 v118, 1.0, v118, vcc
	v_cndmask_b32_e32 v119, 0, v119, vcc
	v_fmac_f32_e32 v119, v3, v118
	v_mul_f32_e32 v2, v2, v118
	v_mov_b32_e32 v3, v119
	s_cmp_lt_i32 s64, s21
	s_cselect_b64 vcc, -1, 0
	s_waitcnt vmcnt(1)
	v_cndmask_b32_e32 v120, 1.0, v120, vcc
	v_cndmask_b32_e32 v121, 0, v121, vcc
	v_fmac_f32_e32 v121, v3, v120
	v_mul_f32_e32 v2, v2, v120
	v_mov_b32_e32 v3, v121
	s_cmp_lt_i32 s68, s21
	s_cselect_b64 vcc, -1, 0
	s_waitcnt vmcnt(0)
	v_cndmask_b32_e32 v122, 1.0, v122, vcc
	v_cndmask_b32_e32 v123, 0, v123, vcc
	v_fmac_f32_e32 v123, v3, v122
	v_mul_f32_e32 v2, v2, v122
	v_mov_b32_e32 v3, v123

; DI unsigned pk2(float lo, float hi) { f32x2 v = {lo, hi}; bf16x2_t b = __builtin_convertvector(v, bf16x2_t); return __builtin_bit_cast(unsigned, b); }
; DI float bf1(bf16_t u) { return __uint_as_float(((unsigned)u) << 16); }
; DI float gelu_tanh(float y) { const float z = 0.7978845608028654f * (y + 0.044715f * y * y * y); const float t = 1.0f - 2.0f * __builtin_amdgcn_rcpf(1.0f + __builtin_amdgcn_exp2f(2.0f * LOG2E * z)); return 0.5f * y * (1.0f + t); }
; DI void rnn_phase(LAS unsigned char* lds, bf16_t* P, const bf16_t* WaT, const bf16_t* WiT, const float* convw, const float* convb, const float* ba, const float* bi, const float* lam,
;                   f32x2* sums, unsigned* au, bool fin, int bx, int G, int tid, int wid, int lane) {
;     ...
;             for (int s2 = 0; s2 < seg; ++s2) h = SGp[s2 * 64 + ch] * h + SGp[512 + s2 * 64 + ch];
; #pragma unroll
;             for (int j = 0; j < 16; ++j) { h = av[j] * h + uv[j]; const float o = h * gelu_tanh(bf1(yv[j])); yp[(size_t)j * DIN] = (bf16_t)(pk2(o, 0.f) & 0xffffu); }
;             par ^= 1;
;         }
;         __syncthreads();
.LBB0_381:
	ds_read2st64_b32 v[4:5], v2 offset1:8
	v_mov_b32_e32 v3, v31
	s_add_i32 s21, s21, -1
	v_add_u32_e32 v2, 0x100, v2
	s_cmp_eq_u32 s21, 0
	s_waitcnt lgkmcnt(0)
	v_mov_b32_e32 v31, v5
	v_fmac_f32_e32 v31, v3, v4
	s_cbranch_scc0 .LBB0_381
	s_branch .LBB0_368
.LBB0_387:
	s_waitcnt lgkmcnt(0)
	s_barrier

; DI float bflo(unsigned u) { return __uint_as_float(u << 16); }
; DI float bfhi(unsigned u) { return __uint_as_float(u & 0xffff0000u); }
; DI void rowpass(const float* hsrc, const bf16_t* mix, const float* gpost, const float* gnext, float* hdst, bf16_t* hb, int gw, int NGW, int lane) {
;     ...
;             for (int j = 0; j < 4; ++j) hv[r][j] = __builtin_nontemporal_load((const f32x4*)(hsrc + (size_t)(m0 + r) * D + 256 * j + 4 * lane));
;         if (mix) {
; #pragma unroll
;             for (int r = 0; r < 2; ++r)
; #pragma unroll
;                 for (int j = 0; j < 4; ++j) { const u32x2 w = __builtin_nontemporal_load((const u32x2*)(mix + (size_t)(m0 + r) * D + 256 * j + 4 * lane)); mv[r][j] = (f32x4){bflo(w.x), bfhi(w.x), bflo(w.y), bfhi(w.y)}; }
;             float ss[2] = {0.f, 0.f};
; #pragma unroll
;             for (int r = 0; r < 2; ++r)
; #pragma unroll
;                 for (int j = 0; j < 4; ++j) ss[r] += (mv[r][j].x * mv[r][j].x + mv[r][j].y * mv[r][j].y) + (mv[r][j].z * mv[r][j].z + mv[r][j].w * mv[r][j].w);
; #pragma unroll
;             for (int o = 1; o < 64; o <<= 1) { ss[0] += __shfl_xor(ss[0], o); ss[1] += __shfl_xor(ss[1], o); }
; #pragma unroll
;             for (int r = 0; r < 2; ++r) { const float rs = __builtin_amdgcn_rsqf(ss[r] * (1.0f / D) + EPS);
; #pragma unroll
;                 for (int j = 0; j < 4; ++j) { const f32x4 gp = *(const f32x4*)(gpost + 256 * j + 4 * lane); hv[r][j] += mv[r][j] * rs * gp; *(f32x4*)(hdst + (size_t)(m0 + r) * D + 256 * j + 4 * lane) = hv[r][j]; } }
.LBB0_401:
	global_load_dwordx2 v[0:1], v[36:37], off offset:0 nt
	global_load_dwordx2 v[2:3], v[36:37], off offset:512 nt
	global_load_dwordx2 v[4:5], v[36:37], off offset:1024 nt
	global_load_dwordx2 v[6:7], v[36:37], off offset:1536 nt
	global_load_dwordx2 v[8:9], v[36:37], off offset:2048 nt
	global_load_dwordx2 v[10:11], v[36:37], off offset:2560 nt
	global_load_dwordx2 v[12:13], v[36:37], off offset:3072 nt
	global_load_dwordx2 v[14:15], v[36:37], off offset:3584 nt
	global_load_dwordx4 v[88:91], v80, s[30:31] offset:0 nt
	global_load_dwordx4 v[92:95], v80, s[30:31] offset:1024 nt
	global_load_dwordx4 v[96:99], v80, s[30:31] offset:2048 nt
	global_load_dwordx4 v[100:103], v80, s[30:31] offset:3072 nt
	global_load_dwordx4 v[104:107], v86, s[30:31] offset:0 nt
	global_load_dwordx4 v[108:111], v86, s[30:31] offset:1024 nt
	global_load_dwordx4 v[112:115], v86, s[30:31] offset:2048 nt
	global_load_dwordx4 v[116:119], v86, s[30:31] offset:3072 nt
	s_waitcnt vmcnt(8)
	v_lshlrev_b32_e32 v48, 16, v0
	v_and_b32_e32 v49, 0xffff0000, v0
	v_lshlrev_b32_e32 v50, 16, v1
	v_and_b32_e32 v51, 0xffff0000, v1
	v_lshlrev_b32_e32 v52, 16, v2
	v_and_b32_e32 v53, 0xffff0000, v2
	v_lshlrev_b32_e32 v54, 16, v3
	v_and_b32_e32 v55, 0xffff0000, v3
	v_lshlrev_b32_e32 v56, 16, v4
	v_and_b32_e32 v57, 0xffff0000, v4
	v_lshlrev_b32_e32 v58, 16, v5
	v_and_b32_e32 v59, 0xffff0000, v5
	v_lshlrev_b32_e32 v60, 16, v6
	v_and_b32_e32 v61, 0xffff0000, v6
	v_lshlrev_b32_e32 v62, 16, v7
	v_and_b32_e32 v63, 0xffff0000, v7
	v_lshlrev_b32_e32 v64, 16, v8
	v_and_b32_e32 v65, 0xffff0000, v8
	v_lshlrev_b32_e32 v66, 16, v9
	v_and_b32_e32 v67, 0xffff0000, v9
	v_lshlrev_b32_e32 v68, 16, v10
	v_and_b32_e32 v69, 0xffff0000, v10
	v_lshlrev_b32_e32 v70, 16, v11
	v_and_b32_e32 v71, 0xffff0000, v11
	v_lshlrev_b32_e32 v72, 16, v12
	v_and_b32_e32 v73, 0xffff0000, v12
	v_lshlrev_b32_e32 v74, 16, v13
	v_and_b32_e32 v75, 0xffff0000, v13
	v_lshlrev_b32_e32 v76, 16, v14
	v_and_b32_e32 v77, 0xffff0000, v14
	v_lshlrev_b32_e32 v78, 16, v15
	v_and_b32_e32 v79, 0xffff0000, v15
	v_pk_mul_f32 v[16:17], v[48:49], v[48:49]
	v_pk_fma_f32 v[16:17], v[50:51], v[50:51], v[16:17]
	v_pk_fma_f32 v[16:17], v[52:53], v[52:53], v[16:17]
	v_pk_fma_f32 v[16:17], v[54:55], v[54:55], v[16:17]
	v_pk_fma_f32 v[16:17], v[56:57], v[56:57], v[16:17]
	v_pk_fma_f32 v[16:17], v[58:59], v[58:59], v[16:17]
	v_pk_fma_f32 v[16:17], v[60:61], v[60:61], v[16:17]
	v_pk_fma_f32 v[16:17], v[62:63], v[62:63], v[16:17]
	v_pk_mul_f32 v[18:19], v[64:65], v[64:65]
	v_pk_fma_f32 v[18:19], v[66:67], v[66:67], v[18:19]
	v_pk_fma_f32 v[18:19], v[68:69], v[68:69], v[18:19]
	v_pk_fma_f32 v[18:19], v[70:71], v[70:71], v[18:19]
	v_pk_fma_f32 v[18:19], v[72:73], v[72:73], v[18:19]
	v_pk_fma_f32 v[18:19], v[74:75], v[74:75], v[18:19]
	v_pk_fma_f32 v[18:19], v[76:77], v[76:77], v[18:19]
	v_pk_fma_f32 v[18:19], v[78:79], v[78:79], v[18:19]
	v_add_f32_e32 v16, v16, v17
	v_add_f32_e32 v18, v18, v19
	s_nop 1
	v_add_f32_dpp v16, v16, v16 quad_perm:[1,0,3,2] row_mask:0xf bank_mask:0xf
	v_add_f32_dpp v18, v18, v18 quad_perm:[1,0,3,2] row_mask:0xf bank_mask:0xf
	s_nop 1
	v_add_f32_dpp v16, v16, v16 quad_perm:[2,3,0,1] row_mask:0xf bank_mask:0xf
	v_add_f32_dpp v18, v18, v18 quad_perm:[2,3,0,1] row_mask:0xf bank_mask:0xf
	s_nop 1
	v_add_f32_dpp v16, v16, v16 row_half_mirror row_mask:0xf bank_mask:0xf
	v_add_f32_dpp v18, v18, v18 row_half_mirror row_mask:0xf bank_mask:0xf
	s_nop 1
	v_add_f32_dpp v16, v16, v16 row_mirror row_mask:0xf bank_mask:0xf
	v_add_f32_dpp v18, v18, v18 row_mirror row_mask:0xf bank_mask:0xf
	s_nop 1
	v_add_f32_dpp v16, v16, v16 row_bcast:15 row_mask:0xa bank_mask:0xf
	v_add_f32_dpp v18, v18, v18 row_bcast:15 row_mask:0xa bank_mask:0xf
	s_nop 1
	v_add_f32_dpp v16, v16, v16 row_bcast:31 row_mask:0xc bank_mask:0xf
	v_add_f32_dpp v18, v18, v18 row_bcast:31 row_mask:0xc bank_mask:0xf
	s_nop 0
	v_readlane_b32 s12, v16, 63
	s_nop 1
	v_mov_b32_e32 v20, s12
	v_readlane_b32 s12, v18, 63
	s_nop 1
	v_mov_b32_e32 v22, s12
	v_fmamk_f32 v20, v20, 0x3a800000, v168
	v_fmamk_f32 v22, v22, 0x3a800000, v168
	v_rsq_f32_e32 v20, v20
	v_rsq_f32_e32 v22, v22
	s_nop 0
	v_pk_mul_f32 v[48:49], v[20:21], v[48:49] op_sel_hi:[0,1]
	v_pk_mul_f32 v[50:51], v[20:21], v[50:51] op_sel_hi:[0,1]
	v_pk_mul_f32 v[52:53], v[20:21], v[52:53] op_sel_hi:[0,1]
	v_pk_mul_f32 v[54:55], v[20:21], v[54:55] op_sel_hi:[0,1]
	v_pk_mul_f32 v[56:57], v[20:21], v[56:57] op_sel_hi:[0,1]
	v_pk_mul_f32 v[58:59], v[20:21], v[58:59] op_sel_hi:[0,1]
	v_pk_mul_f32 v[60:61], v[20:21], v[60:61] op_sel_hi:[0,1]
	v_pk_mul_f32 v[62:63], v[20:21], v[62:63] op_sel_hi:[0,1]
	v_pk_mul_f32 v[64:65], v[22:23], v[64:65] op_sel_hi:[0,1]
	v_pk_mul_f32 v[66:67], v[22:23], v[66:67] op_sel_hi:[0,1]
	v_pk_mul_f32 v[68:69], v[22:23], v[68:69] op_sel_hi:[0,1]
	v_pk_mul_f32 v[70:71], v[22:23], v[70:71] op_sel_hi:[0,1]
	v_pk_mul_f32 v[72:73], v[22:23], v[72:73] op_sel_hi:[0,1]
	v_pk_mul_f32 v[74:75], v[22:23], v[74:75] op_sel_hi:[0,1]
	v_pk_mul_f32 v[76:77], v[22:23], v[76:77] op_sel_hi:[0,1]
	v_pk_mul_f32 v[78:79], v[22:23], v[78:79] op_sel_hi:[0,1]
	s_waitcnt vmcnt(0)
	v_pk_fma_f32 v[88:89], v[48:49], v[120:121], v[88:89]
	v_pk_fma_f32 v[90:91], v[50:51], v[122:123], v[90:91]
	global_store_dwordx4 v80, v[88:91], s[36:37] offset:0 nt
	v_pk_fma_f32 v[92:93], v[52:53], v[124:125], v[92:93]
	v_pk_fma_f32 v[94:95], v[54:55], v[126:127], v[94:95]
	global_store_dwordx4 v80, v[92:95], s[36:37] offset:1024 nt
	v_pk_fma_f32 v[96:97], v[56:57], v[128:129], v[96:97]
	v_pk_fma_f32 v[98:99], v[58:59], v[130:131], v[98:99]
	global_store_dwordx4 v80, v[96:99], s[36:37] offset:2048 nt
	v_pk_fma_f32 v[100:101], v[60:61], v[132:133], v[100:101]
	v_pk_fma_f32 v[102:103], v[62:63], v[134:135], v[102:103]
	global_store_dwordx4 v80, v[100:103], s[36:37] offset:3072 nt
	v_pk_fma_f32 v[104:105], v[64:65], v[120:121], v[104:105]
	v_pk_fma_f32 v[106:107], v[66:67], v[122:123], v[106:107]
	global_store_dwordx4 v86, v[104:107], s[36:37] offset:0 nt
	v_pk_fma_f32 v[108:109], v[68:69], v[124:125], v[108:109]
	v_pk_fma_f32 v[110:111], v[70:71], v[126:127], v[110:111]
	global_store_dwordx4 v86, v[108:111], s[36:37] offset:1024 nt
	v_pk_fma_f32 v[112:113], v[72:73], v[128:129], v[112:113]
	v_pk_fma_f32 v[114:115], v[74:75], v[130:131], v[114:115]
	global_store_dwordx4 v86, v[112:115], s[36:37] offset:2048 nt
	v_pk_fma_f32 v[116:117], v[76:77], v[132:133], v[116:117]
	v_pk_fma_f32 v[118:119], v[78:79], v[134:135], v[118:119]
	global_store_dwordx4 v86, v[116:119], s[36:37] offset:3072 nt
	s_andn2_b64 vcc, exec, s[0:1]
	s_cbranch_vccnz .LBB0_400
; DI unsigned pk2(float lo, float hi) { f32x2 v = {lo, hi}; bf16x2_t b = __builtin_convertvector(v, bf16x2_t); return __builtin_bit_cast(unsigned, b); }
; DI void rowpass(const float* hsrc, const bf16_t* mix, const float* gpost, const float* gnext, float* hdst, bf16_t* hb, int gw, int NGW, int lane) {
;     ...
;         if (gnext) {
;             float ss[2] = {0.f, 0.f};
; #pragma unroll
;             for (int r = 0; r < 2; ++r)
; #pragma unroll
;                 for (int j = 0; j < 4; ++j) ss[r] += (hv[r][j].x * hv[r][j].x + hv[r][j].y * hv[r][j].y) + (hv[r][j].z * hv[r][j].z + hv[r][j].w * hv[r][j].w);
; #pragma unroll
;             for (int o = 1; o < 64; o <<= 1) { ss[0] += __shfl_xor(ss[0], o); ss[1] += __shfl_xor(ss[1], o); }
; #pragma unroll
;             for (int r = 0; r < 2; ++r) { const float rs = __builtin_amdgcn_rsqf(ss[r] * (1.0f / D) + EPS);
; #pragma unroll
;                 for (int j = 0; j < 4; ++j) { const f32x4 gn = *(const f32x4*)(gnext + 256 * j + 4 * lane); const f32x4 o = hv[r][j] * rs * gn;
;                     u32x2 w; w.x = pk2(o.x, o.y); w.y = pk2(o.z, o.w); *(u32x2*)(hb + (size_t)(m0 + r) * D + 256 * j + 4 * lane) = w; } }
	v_pk_mul_f32 v[16:17], v[88:89], v[88:89]
	v_pk_fma_f32 v[16:17], v[90:91], v[90:91], v[16:17]
	v_pk_fma_f32 v[16:17], v[92:93], v[92:93], v[16:17]
	v_pk_fma_f32 v[16:17], v[94:95], v[94:95], v[16:17]
	v_pk_fma_f32 v[16:17], v[96:97], v[96:97], v[16:17]
	v_pk_fma_f32 v[16:17], v[98:99], v[98:99], v[16:17]
	v_pk_fma_f32 v[16:17], v[100:101], v[100:101], v[16:17]
	v_pk_fma_f32 v[16:17], v[102:103], v[102:103], v[16:17]
	v_pk_mul_f32 v[18:19], v[104:105], v[104:105]
	v_pk_fma_f32 v[18:19], v[106:107], v[106:107], v[18:19]
	v_pk_fma_f32 v[18:19], v[108:109], v[108:109], v[18:19]
	v_pk_fma_f32 v[18:19], v[110:111], v[110:111], v[18:19]
	v_pk_fma_f32 v[18:19], v[112:113], v[112:113], v[18:19]
	v_pk_fma_f32 v[18:19], v[114:115], v[114:115], v[18:19]
	v_pk_fma_f32 v[18:19], v[116:117], v[116:117], v[18:19]
	v_pk_fma_f32 v[18:19], v[118:119], v[118:119], v[18:19]
	v_add_f32_e32 v16, v16, v17
	v_add_f32_e32 v18, v18, v19
	s_nop 1
	v_add_f32_dpp v16, v16, v16 quad_perm:[1,0,3,2] row_mask:0xf bank_mask:0xf
	v_add_f32_dpp v18, v18, v18 quad_perm:[1,0,3,2] row_mask:0xf bank_mask:0xf
	s_nop 1
	v_add_f32_dpp v16, v16, v16 quad_perm:[2,3,0,1] row_mask:0xf bank_mask:0xf
	v_add_f32_dpp v18, v18, v18 quad_perm:[2,3,0,1] row_mask:0xf bank_mask:0xf
	s_nop 1
	v_add_f32_dpp v16, v16, v16 row_half_mirror row_mask:0xf bank_mask:0xf
	v_add_f32_dpp v18, v18, v18 row_half_mirror row_mask:0xf bank_mask:0xf
	s_nop 1
	v_add_f32_dpp v16, v16, v16 row_mirror row_mask:0xf bank_mask:0xf
	v_add_f32_dpp v18, v18, v18 row_mirror row_mask:0xf bank_mask:0xf
	s_nop 1
	v_add_f32_dpp v16, v16, v16 row_bcast:15 row_mask:0xa bank_mask:0xf
	v_add_f32_dpp v18, v18, v18 row_bcast:15 row_mask:0xa bank_mask:0xf
	s_nop 1
	v_add_f32_dpp v16, v16, v16 row_bcast:31 row_mask:0xc bank_mask:0xf
	v_add_f32_dpp v18, v18, v18 row_bcast:31 row_mask:0xc bank_mask:0xf
	s_nop 0
	v_readlane_b32 s12, v16, 63
	s_nop 1
	v_mov_b32_e32 v20, s12
	v_readlane_b32 s12, v18, 63
	s_nop 1
	v_mov_b32_e32 v22, s12
	v_fmamk_f32 v20, v20, 0x3a800000, v168
	v_fmamk_f32 v22, v22, 0x3a800000, v168
	v_rsq_f32_e32 v20, v20
	v_rsq_f32_e32 v22, v22
	v_add_co_u32_e32 v82, vcc, 0xf2000000, v36
	s_nop 1
	v_addc_co_u32_e32 v83, vcc, -1, v37, vcc
	v_pk_mul_f32 v[48:49], v[88:89], v[20:21] op_sel_hi:[1,0]
	v_pk_mul_f32 v[50:51], v[90:91], v[20:21] op_sel_hi:[1,0]
	v_pk_mul_f32 v[48:49], v[48:49], v[176:177]
	v_pk_mul_f32 v[50:51], v[50:51], v[178:179]
	v_cvt_pk_bf16_f32 v0, v48, v49
	v_cvt_pk_bf16_f32 v1, v50, v51
	global_store_dwordx2 v[82:83], v[0:1], off offset:0
	v_pk_mul_f32 v[52:53], v[92:93], v[20:21] op_sel_hi:[1,0]
	v_pk_mul_f32 v[54:55], v[94:95], v[20:21] op_sel_hi:[1,0]
	v_pk_mul_f32 v[52:53], v[52:53], v[180:181]
	v_pk_mul_f32 v[54:55], v[54:55], v[182:183]
	v_cvt_pk_bf16_f32 v2, v52, v53
	v_cvt_pk_bf16_f32 v3, v54, v55
	global_store_dwordx2 v[82:83], v[2:3], off offset:512
	v_pk_mul_f32 v[56:57], v[96:97], v[20:21] op_sel_hi:[1,0]
	v_pk_mul_f32 v[58:59], v[98:99], v[20:21] op_sel_hi:[1,0]
	v_pk_mul_f32 v[56:57], v[56:57], v[184:185]
	v_pk_mul_f32 v[58:59], v[58:59], v[186:187]
	v_cvt_pk_bf16_f32 v4, v56, v57
	v_cvt_pk_bf16_f32 v5, v58, v59
	global_store_dwordx2 v[82:83], v[4:5], off offset:1024
	v_pk_mul_f32 v[60:61], v[100:101], v[20:21] op_sel_hi:[1,0]
	v_pk_mul_f32 v[62:63], v[102:103], v[20:21] op_sel_hi:[1,0]
	v_pk_mul_f32 v[60:61], v[60:61], v[188:189]
	v_pk_mul_f32 v[62:63], v[62:63], v[190:191]
	v_cvt_pk_bf16_f32 v6, v60, v61
	v_cvt_pk_bf16_f32 v7, v62, v63
	global_store_dwordx2 v[82:83], v[6:7], off offset:1536
	v_pk_mul_f32 v[64:65], v[104:105], v[22:23] op_sel_hi:[1,0]
	v_pk_mul_f32 v[66:67], v[106:107], v[22:23] op_sel_hi:[1,0]
	v_pk_mul_f32 v[64:65], v[64:65], v[176:177]
	v_pk_mul_f32 v[66:67], v[66:67], v[178:179]
	v_cvt_pk_bf16_f32 v8, v64, v65
	v_cvt_pk_bf16_f32 v9, v66, v67
	global_store_dwordx2 v[82:83], v[8:9], off offset:2048
	v_pk_mul_f32 v[68:69], v[108:109], v[22:23] op_sel_hi:[1,0]
	v_pk_mul_f32 v[70:71], v[110:111], v[22:23] op_sel_hi:[1,0]
	v_pk_mul_f32 v[68:69], v[68:69], v[180:181]
	v_pk_mul_f32 v[70:71], v[70:71], v[182:183]
	v_cvt_pk_bf16_f32 v10, v68, v69
	v_cvt_pk_bf16_f32 v11, v70, v71
	global_store_dwordx2 v[82:83], v[10:11], off offset:2560
	v_pk_mul_f32 v[72:73], v[112:113], v[22:23] op_sel_hi:[1,0]
	v_pk_mul_f32 v[74:75], v[114:115], v[22:23] op_sel_hi:[1,0]
	v_pk_mul_f32 v[72:73], v[72:73], v[184:185]
	v_pk_mul_f32 v[74:75], v[74:75], v[186:187]
	v_cvt_pk_bf16_f32 v12, v72, v73
	v_cvt_pk_bf16_f32 v13, v74, v75
	global_store_dwordx2 v[82:83], v[12:13], off offset:3072
	v_pk_mul_f32 v[76:77], v[116:117], v[22:23] op_sel_hi:[1,0]
	v_pk_mul_f32 v[78:79], v[118:119], v[22:23] op_sel_hi:[1,0]
	v_pk_mul_f32 v[76:77], v[76:77], v[188:189]
	v_pk_mul_f32 v[78:79], v[78:79], v[190:191]
	v_cvt_pk_bf16_f32 v14, v76, v77
	v_cvt_pk_bf16_f32 v15, v78, v79
	global_store_dwordx2 v[82:83], v[14:15], off offset:3584
	s_branch .LBB0_400

; #define PG8_STAGE(bufoff, gbase, voff) do { _Pragma("unroll") for (int _i = 0; _i < 2; ++_i) \
;         __builtin_amdgcn_global_load_lds((const unsigned*)((const char*)(gbase) + (voff)[_i]), (LAS unsigned*)(lds + (bufoff) + ldsw + _i * 8192), 16, 0, 0); } while (0)
; #define PG8_LDA(dst, b, h) do { _Pragma("unroll") for (int m = 0; m < 4; ++m) _Pragma("unroll") for (int k = 0; k < 2; ++k) dst[m][k] = *(const LAS bf16x8*)(lds + PG8_SA(b, h) + aoff + m * 2048 + k * 1024); } while (0)
; #define PG8_LDB(dst, b, h) do { _Pragma("unroll") for (int n = 0; n < 2; ++n) _Pragma("unroll") for (int k = 0; k < 2; ++k) dst[n][k] = *(const LAS bf16x8*)(lds + PG8_SB(b, h) + boff + n * 2048 + k * 1024); } while (0)
; #define PG8_MMA(ai, bj, At, Bt) do { __builtin_amdgcn_s_setprio(1); _Pragma("unroll") for (int m = 0; m < 4; ++m) _Pragma("unroll") for (int n = 0; n < 2; ++n) _Pragma("unroll") for (int k = 0; k < 2; ++k) \
;         acc[ai][bj][m][n] = __builtin_amdgcn_mfma_f32_16x16x32_bf16(Bt[n][k], At[m][k], acc[ai][bj][m][n], 0, 0, 0); __builtin_amdgcn_s_setprio(0); } while (0)
; #define PG8_WAIT_V(n) asm volatile("s_waitcnt vmcnt(" #n ")" ::: "memory")
; #define PG8_WAIT_L(n) asm volatile("s_waitcnt lgkmcnt(" #n ")" ::: "memory")
; #define PG8_BAR __builtin_amdgcn_s_barrier()
; DI void gemm_phase(LAS unsigned char* lds, int ph, unsigned char* ws, unsigned char* wg, int l, const float* pscale, int G, int cidx, int nx) {
;     ...
;             const char* a1 = PG8_KA(t + 1);
;             const char* a2 = last ? nA : PG8_KA(t + 2); const char* b2 = last ? nB : PG8_KB(t + 2);
;             const char* a3 = a2 + kstep; const char* b3 = b2 + kstep;
;             if (zAb != 0 && t != 0 && (t & ntzm) == 0) { unsigned char* wsx = ws; asm volatile("" : "+s"(wsx)); int frx = fr; asm volatile("" : "+v"(frx)); merge_carry(acc, wsx, cur, (t >> lz) - 1, wr, wc, frx, fq); }
;             PG8_LDB(B0, 0, 0); PG8_LDB(B1, 0, 1); PG8_SCHED; PG8_LDA(At, 0, 0); PG8_STAGE(PG8_SA(1, 1), a1 + hstepA, voffA);
;             PG8_WAIT_V(8); PG8_WAIT_L(0); PG8_BAR; PG8_MMA(0, 0, At, B0); PG8_MMA(0, 1, At, B1); PG8_BAR; PG8_SCHED;
;             PG8_LDA(At, 0, 1); PG8_STAGE(PG8_SB(0, 0), b2, voffB); PG8_STAGE(PG8_SB(0, 1), b2 + hstepB, voffB); PG8_STAGE(PG8_SA(0, 0), a2, voffA);
;             PG8_WAIT_V(8); PG8_WAIT_L(0); PG8_BAR; PG8_MMA(1, 0, At, B0); PG8_MMA(1, 1, At, B1); PG8_BAR; PG8_SCHED;
.LBB0_500:
	s_add_i32 s12, s38, 1
	s_lshr_b32 s18, s12, s76
	s_mul_i32 s19, s53, s18
	s_mul_hi_u32 s20, s52, s18
	s_add_i32 s20, s20, s19
	s_mul_i32 s18, s52, s18
	s_add_u32 s18, s42, s18
	s_addc_u32 s19, s43, s20
	s_and_b32 s12, s12, s83
	s_lshl_b32 s12, s12, 7
	s_add_u32 s12, s18, s12
	s_addc_u32 s19, s19, 0
	v_add_u32_e32 v80, s91, v173
	s_add_i32 s20, 0, 0x14000
	ds_read_b128 v[132:135], v80
	ds_read_b128 v[136:139], v80 offset:1024
	ds_read_b128 v[142:145], v80 offset:2048
	ds_read_b128 v[158:161], v80 offset:3072
	v_add_u32_e32 v80, s20, v173
	ds_read_b128 v[176:179], v80
	ds_read_b128 v[180:183], v80 offset:1024
	ds_read_b128 v[184:187], v80 offset:2048
	ds_read_b128 v[188:191], v80 offset:3072
	s_add_u32 s18, s12, s7
	s_addc_u32 s19, s19, 0
	s_add_i32 m0, s79, 0xc000
	ds_read_b128 v[192:195], v174
	ds_read_b128 v[196:199], v174 offset:1024
	ds_read_b128 v[200:203], v174 offset:2048
	ds_read_b128 v[204:207], v174 offset:3072
	ds_read_b128 v[208:211], v174 offset:4096
	ds_read_b128 v[212:215], v174 offset:5120
	ds_read_b128 v[216:219], v174 offset:6144
	ds_read_b128 v[220:223], v174 offset:7168
	global_load_lds_dwordx4 v150, s[18:19]
	s_add_i32 m0, s79, 0xe000
	s_nop 0
	global_load_lds_dwordx4 v154, s[18:19]
	s_waitcnt vmcnt(8)
	s_waitcnt lgkmcnt(0)
	s_barrier
	s_setprio 1
	s_waitcnt lgkmcnt(0)
	v_mfma_f32_16x16x32_bf16 v[128:131], v[132:135], v[192:195], v[128:131]
	v_mfma_f32_16x16x32_bf16 v[124:127], v[142:145], v[192:195], v[124:127]
	v_mfma_f32_16x16x32_bf16 v[112:115], v[132:135], v[200:203], v[112:115]
	v_mfma_f32_16x16x32_bf16 v[108:111], v[142:145], v[200:203], v[108:111]
	v_mfma_f32_16x16x32_bf16 v[96:99], v[132:135], v[208:211], v[96:99]
	v_mfma_f32_16x16x32_bf16 v[92:95], v[142:145], v[208:211], v[92:95]
	v_mfma_f32_16x16x32_bf16 v[76:79], v[132:135], v[216:219], v[76:79]
	v_mfma_f32_16x16x32_bf16 v[72:75], v[142:145], v[216:219], v[72:75]
	v_mfma_f32_16x16x32_bf16 v[128:131], v[136:139], v[196:199], v[128:131]
	v_mfma_f32_16x16x32_bf16 v[124:127], v[158:161], v[196:199], v[124:127]
	v_mfma_f32_16x16x32_bf16 v[112:115], v[136:139], v[204:207], v[112:115]
	v_mfma_f32_16x16x32_bf16 v[108:111], v[158:161], v[204:207], v[108:111]
	v_mfma_f32_16x16x32_bf16 v[96:99], v[136:139], v[212:215], v[96:99]
	v_mfma_f32_16x16x32_bf16 v[92:95], v[158:161], v[212:215], v[92:95]
	v_mfma_f32_16x16x32_bf16 v[76:79], v[136:139], v[220:223], v[76:79]
	v_mfma_f32_16x16x32_bf16 v[72:75], v[158:161], v[220:223], v[72:75]
	s_setprio 0
	s_setprio 1
	v_mfma_f32_16x16x32_bf16 v[120:123], v[176:179], v[192:195], v[120:123]
	v_mfma_f32_16x16x32_bf16 v[116:119], v[184:187], v[192:195], v[116:119]
	v_mfma_f32_16x16x32_bf16 v[104:107], v[176:179], v[200:203], v[104:107]
	v_mfma_f32_16x16x32_bf16 v[100:103], v[184:187], v[200:203], v[100:103]
	v_mfma_f32_16x16x32_bf16 v[88:91], v[176:179], v[208:211], v[88:91]
	v_mfma_f32_16x16x32_bf16 v[82:85], v[184:187], v[208:211], v[84:87]
	v_mfma_f32_16x16x32_bf16 v[68:71], v[176:179], v[216:219], v[68:71]
	v_mfma_f32_16x16x32_bf16 v[64:67], v[184:187], v[216:219], v[64:67]
	v_mfma_f32_16x16x32_bf16 v[120:123], v[180:183], v[196:199], v[120:123]
	v_mfma_f32_16x16x32_bf16 v[116:119], v[188:191], v[196:199], v[116:119]
	v_mfma_f32_16x16x32_bf16 v[104:107], v[180:183], v[204:207], v[104:107]
	v_mfma_f32_16x16x32_bf16 v[100:103], v[188:191], v[204:207], v[100:103]
	v_mfma_f32_16x16x32_bf16 v[88:91], v[180:183], v[212:215], v[88:91]
	v_mfma_f32_16x16x32_bf16 v[82:85], v[188:191], v[212:215], v[82:85]
	v_mfma_f32_16x16x32_bf16 v[68:71], v[180:183], v[220:223], v[68:71]
	v_mfma_f32_16x16x32_bf16 v[64:67], v[188:191], v[220:223], v[64:67]
	s_setprio 0
	s_barrier
	s_add_i32 s12, s91, s78
	s_mov_b32 m0, s12
	ds_read_b128 v[192:195], v174 offset:16384
	ds_read_b128 v[196:199], v174 offset:17408
	ds_read_b128 v[200:203], v174 offset:18432
	ds_read_b128 v[204:207], v174 offset:19456
	ds_read_b128 v[208:211], v174 offset:20480
	ds_read_b128 v[212:215], v174 offset:21504
	ds_read_b128 v[216:219], v174 offset:22528
	ds_read_b128 v[220:223], v174 offset:23552
	global_load_lds_dwordx4 v152, s[64:65]
	s_add_i32 m0, s12, 0x2000
	s_add_u32 s18, s64, s77
	s_addc_u32 s19, s65, 0
	s_add_i32 s12, s20, s78
	global_load_lds_dwordx4 v156, s[64:65]
	s_mov_b32 m0, s12
	s_nop 0
	global_load_lds_dwordx4 v152, s[18:19]
	s_add_i32 m0, s12, 0x2000
	s_nop 0
	global_load_lds_dwordx4 v156, s[18:19]
	s_mov_b32 m0, s79
	s_nop 0
	global_load_lds_dwordx4 v150, s[0:1]
	s_mov_b32 m0, s80
	s_nop 0
	global_load_lds_dwordx4 v154, s[0:1]
	s_waitcnt vmcnt(8)
	s_waitcnt lgkmcnt(0)
	s_barrier
; #define PG8_STAGE(bufoff, gbase, voff) do { _Pragma("unroll") for (int _i = 0; _i < 2; ++_i) \
;         __builtin_amdgcn_global_load_lds((const unsigned*)((const char*)(gbase) + (voff)[_i]), (LAS unsigned*)(lds + (bufoff) + ldsw + _i * 8192), 16, 0, 0); } while (0)
; #define PG8_LDA(dst, b, h) do { _Pragma("unroll") for (int m = 0; m < 4; ++m) _Pragma("unroll") for (int k = 0; k < 2; ++k) dst[m][k] = *(const LAS bf16x8*)(lds + PG8_SA(b, h) + aoff + m * 2048 + k * 1024); } while (0)
; #define PG8_LDB(dst, b, h) do { _Pragma("unroll") for (int n = 0; n < 2; ++n) _Pragma("unroll") for (int k = 0; k < 2; ++k) dst[n][k] = *(const LAS bf16x8*)(lds + PG8_SB(b, h) + boff + n * 2048 + k * 1024); } while (0)
; #define PG8_MMA(ai, bj, At, Bt) do { __builtin_amdgcn_s_setprio(1); _Pragma("unroll") for (int m = 0; m < 4; ++m) _Pragma("unroll") for (int n = 0; n < 2; ++n) _Pragma("unroll") for (int k = 0; k < 2; ++k) \
;         acc[ai][bj][m][n] = __builtin_amdgcn_mfma_f32_16x16x32_bf16(Bt[n][k], At[m][k], acc[ai][bj][m][n], 0, 0, 0); __builtin_amdgcn_s_setprio(0); } while (0)
; #define PG8_WAIT_V(n) asm volatile("s_waitcnt vmcnt(" #n ")" ::: "memory")
; #define PG8_WAIT_L(n) asm volatile("s_waitcnt lgkmcnt(" #n ")" ::: "memory")
; #define PG8_BAR __builtin_amdgcn_s_barrier()
; #define PG8_SCHED __builtin_amdgcn_sched_barrier(0)
; DI void gemm_phase(LAS unsigned char* lds, int ph, unsigned char* ws, unsigned char* wg, int l, const float* pscale, int G, int cidx, int nx) {
;     ...
;             PG8_WAIT_V(8); PG8_WAIT_L(0); PG8_BAR; PG8_MMA(1, 0, At, B0); PG8_MMA(1, 1, At, B1); PG8_BAR; PG8_SCHED;
;             PG8_LDB(B0, 1, 0); PG8_LDB(B1, 1, 1); PG8_SCHED; PG8_LDA(At, 1, 0); PG8_STAGE(PG8_SA(0, 1), a2 + hstepA, voffA);
;             PG8_WAIT_V(8); PG8_WAIT_L(0); PG8_BAR; PG8_MMA(0, 0, At, B0); PG8_MMA(0, 1, At, B1); PG8_BAR; PG8_SCHED;
	s_setprio 1
	s_waitcnt lgkmcnt(0)
	v_mfma_f32_16x16x32_bf16 v[60:63], v[132:135], v[192:195], v[60:63]
	v_mfma_f32_16x16x32_bf16 v[56:59], v[142:145], v[192:195], v[56:59]
	v_mfma_f32_16x16x32_bf16 v[44:47], v[132:135], v[200:203], v[44:47]
	v_mfma_f32_16x16x32_bf16 v[40:43], v[142:145], v[200:203], v[40:43]
	v_mfma_f32_16x16x32_bf16 v[28:31], v[132:135], v[208:211], v[28:31]
	v_mfma_f32_16x16x32_bf16 v[24:27], v[142:145], v[208:211], v[24:27]
	v_mfma_f32_16x16x32_bf16 v[12:15], v[132:135], v[216:219], v[12:15]
	v_mfma_f32_16x16x32_bf16 v[8:11], v[142:145], v[216:219], v[8:11]
	v_mfma_f32_16x16x32_bf16 v[60:63], v[136:139], v[196:199], v[60:63]
	v_mfma_f32_16x16x32_bf16 v[56:59], v[158:161], v[196:199], v[56:59]
	v_mfma_f32_16x16x32_bf16 v[44:47], v[136:139], v[204:207], v[44:47]
	v_mfma_f32_16x16x32_bf16 v[40:43], v[158:161], v[204:207], v[40:43]
	v_mfma_f32_16x16x32_bf16 v[28:31], v[136:139], v[212:215], v[28:31]
	v_mfma_f32_16x16x32_bf16 v[24:27], v[158:161], v[212:215], v[24:27]
	v_mfma_f32_16x16x32_bf16 v[12:15], v[136:139], v[220:223], v[12:15]
	v_mfma_f32_16x16x32_bf16 v[8:11], v[158:161], v[220:223], v[8:11]
	s_setprio 0
	s_setprio 1
	v_mfma_f32_16x16x32_bf16 v[52:55], v[176:179], v[192:195], v[52:55]
	v_mfma_f32_16x16x32_bf16 v[48:51], v[184:187], v[192:195], v[48:51]
	v_mfma_f32_16x16x32_bf16 v[36:39], v[176:179], v[200:203], v[36:39]
	v_mfma_f32_16x16x32_bf16 v[32:35], v[184:187], v[200:203], v[32:35]
	v_mfma_f32_16x16x32_bf16 v[20:23], v[176:179], v[208:211], v[20:23]
	v_mfma_f32_16x16x32_bf16 v[16:19], v[184:187], v[208:211], v[16:19]
	v_mfma_f32_16x16x32_bf16 v[4:7], v[176:179], v[216:219], v[4:7]
	v_mfma_f32_16x16x32_bf16 v[0:3], v[184:187], v[216:219], v[0:3]
	v_mfma_f32_16x16x32_bf16 v[52:55], v[180:183], v[196:199], v[52:55]
	v_mfma_f32_16x16x32_bf16 v[48:51], v[188:191], v[196:199], v[48:51]
	v_mfma_f32_16x16x32_bf16 v[36:39], v[180:183], v[204:207], v[36:39]
	v_mfma_f32_16x16x32_bf16 v[32:35], v[188:191], v[204:207], v[32:35]
	v_mfma_f32_16x16x32_bf16 v[20:23], v[180:183], v[212:215], v[20:23]
	v_mfma_f32_16x16x32_bf16 v[16:19], v[188:191], v[212:215], v[16:19]
	v_mfma_f32_16x16x32_bf16 v[4:7], v[180:183], v[220:223], v[4:7]
	v_mfma_f32_16x16x32_bf16 v[0:3], v[188:191], v[220:223], v[0:3]
	s_setprio 0
	s_barrier
	s_add_i32 s12, 0, 0x18000
	v_add_u32_e32 v80, s12, v173
	s_add_i32 s18, 0, 0x1c000
	ds_read_b128 v[132:135], v80
	ds_read_b128 v[136:139], v80 offset:1024
	ds_read_b128 v[142:145], v80 offset:2048
	ds_read_b128 v[158:161], v80 offset:3072
	v_add_u32_e32 v80, s18, v173
	ds_read_b128 v[176:179], v80
	ds_read_b128 v[180:183], v80 offset:1024
	ds_read_b128 v[184:187], v80 offset:2048
	ds_read_b128 v[188:191], v80 offset:3072
	s_add_u32 s0, s0, s7
	s_addc_u32 s1, s1, 0
	s_mov_b32 m0, s81
	ds_read_b128 v[192:195], v174 offset:32768
	ds_read_b128 v[196:199], v174 offset:33792
	ds_read_b128 v[200:203], v174 offset:34816
	ds_read_b128 v[204:207], v174 offset:35840
	ds_read_b128 v[208:211], v174 offset:36864
	ds_read_b128 v[212:215], v174 offset:37888
	ds_read_b128 v[216:219], v174 offset:38912
	ds_read_b128 v[220:223], v174 offset:39936
	global_load_lds_dwordx4 v150, s[0:1]
	s_mov_b32 m0, s82
	s_nop 0
	global_load_lds_dwordx4 v154, s[0:1]
	s_waitcnt vmcnt(8)
	s_waitcnt lgkmcnt(0)
	s_barrier
	s_setprio 1
	s_waitcnt lgkmcnt(0)
	v_mfma_f32_16x16x32_bf16 v[128:131], v[132:135], v[192:195], v[128:131]
	v_mfma_f32_16x16x32_bf16 v[124:127], v[142:145], v[192:195], v[124:127]
	v_mfma_f32_16x16x32_bf16 v[112:115], v[132:135], v[200:203], v[112:115]
	v_mfma_f32_16x16x32_bf16 v[108:111], v[142:145], v[200:203], v[108:111]
	v_mfma_f32_16x16x32_bf16 v[96:99], v[132:135], v[208:211], v[96:99]
	v_mfma_f32_16x16x32_bf16 v[92:95], v[142:145], v[208:211], v[92:95]
	v_mfma_f32_16x16x32_bf16 v[76:79], v[132:135], v[216:219], v[76:79]
	v_mfma_f32_16x16x32_bf16 v[72:75], v[142:145], v[216:219], v[72:75]
	v_mfma_f32_16x16x32_bf16 v[128:131], v[136:139], v[196:199], v[128:131]
	v_mfma_f32_16x16x32_bf16 v[124:127], v[158:161], v[196:199], v[124:127]
	v_mfma_f32_16x16x32_bf16 v[112:115], v[136:139], v[204:207], v[112:115]
	v_mfma_f32_16x16x32_bf16 v[108:111], v[158:161], v[204:207], v[108:111]
	v_mfma_f32_16x16x32_bf16 v[96:99], v[136:139], v[212:215], v[96:99]
	v_mfma_f32_16x16x32_bf16 v[92:95], v[158:161], v[212:215], v[92:95]
	v_mfma_f32_16x16x32_bf16 v[76:79], v[136:139], v[220:223], v[76:79]
	v_mfma_f32_16x16x32_bf16 v[72:75], v[158:161], v[220:223], v[72:75]
	s_setprio 0
	s_setprio 1
	v_mfma_f32_16x16x32_bf16 v[120:123], v[176:179], v[192:195], v[120:123]
	v_mfma_f32_16x16x32_bf16 v[116:119], v[184:187], v[192:195], v[116:119]
	v_mfma_f32_16x16x32_bf16 v[104:107], v[176:179], v[200:203], v[104:107]
	v_mfma_f32_16x16x32_bf16 v[100:103], v[184:187], v[200:203], v[100:103]
	v_mfma_f32_16x16x32_bf16 v[86:89], v[176:179], v[208:211], v[88:91]
	v_mfma_f32_16x16x32_bf16 v[82:85], v[184:187], v[208:211], v[82:85]
	v_mfma_f32_16x16x32_bf16 v[68:71], v[176:179], v[216:219], v[68:71]
	v_mfma_f32_16x16x32_bf16 v[64:67], v[184:187], v[216:219], v[64:67]
	v_mfma_f32_16x16x32_bf16 v[120:123], v[180:183], v[196:199], v[120:123]
	v_mfma_f32_16x16x32_bf16 v[116:119], v[188:191], v[196:199], v[116:119]
	v_mfma_f32_16x16x32_bf16 v[104:107], v[180:183], v[204:207], v[104:107]
	v_mfma_f32_16x16x32_bf16 v[100:103], v[188:191], v[204:207], v[100:103]
	v_mfma_f32_16x16x32_bf16 v[88:91], v[180:183], v[212:215], v[86:89]
	v_mfma_f32_16x16x32_bf16 v[84:87], v[188:191], v[212:215], v[82:85]
	v_mfma_f32_16x16x32_bf16 v[68:71], v[180:183], v[220:223], v[68:71]
	v_mfma_f32_16x16x32_bf16 v[64:67], v[188:191], v[220:223], v[64:67]
	s_setprio 0
	s_barrier
; #define PG8_STAGE(bufoff, gbase, voff) do { _Pragma("unroll") for (int _i = 0; _i < 2; ++_i) \
;         __builtin_amdgcn_global_load_lds((const unsigned*)((const char*)(gbase) + (voff)[_i]), (LAS unsigned*)(lds + (bufoff) + ldsw + _i * 8192), 16, 0, 0); } while (0)
; #define PG8_LDA(dst, b, h) do { _Pragma("unroll") for (int m = 0; m < 4; ++m) _Pragma("unroll") for (int k = 0; k < 2; ++k) dst[m][k] = *(const LAS bf16x8*)(lds + PG8_SA(b, h) + aoff + m * 2048 + k * 1024); } while (0)
; #define PG8_MMA(ai, bj, At, Bt) do { __builtin_amdgcn_s_setprio(1); _Pragma("unroll") for (int m = 0; m < 4; ++m) _Pragma("unroll") for (int n = 0; n < 2; ++n) _Pragma("unroll") for (int k = 0; k < 2; ++k) \
;         acc[ai][bj][m][n] = __builtin_amdgcn_mfma_f32_16x16x32_bf16(Bt[n][k], At[m][k], acc[ai][bj][m][n], 0, 0, 0); __builtin_amdgcn_s_setprio(0); } while (0)
; #define PG8_WAIT_V(n) asm volatile("s_waitcnt vmcnt(" #n ")" ::: "memory")
; #define PG8_WAIT_L(n) asm volatile("s_waitcnt lgkmcnt(" #n ")" ::: "memory")
; #define PG8_BAR __builtin_amdgcn_s_barrier()
; #define PG8_SCHED __builtin_amdgcn_sched_barrier(0)
; DI void gemm_phase(LAS unsigned char* lds, int ph, unsigned char* ws, unsigned char* wg, int l, const float* pscale, int G, int cidx, int nx) {
;     ...
;         for (int t = 0; t < nt; t += 2) {
;     ...
;             PG8_LDA(At, 1, 1); PG8_STAGE(PG8_SB(1, 0), b3, voffB); PG8_STAGE(PG8_SB(1, 1), b3 + hstepB, voffB); PG8_STAGE(PG8_SA(1, 0), a3, voffA);
;             PG8_WAIT_V(8); PG8_WAIT_L(0); PG8_BAR; PG8_MMA(1, 0, At, B0); PG8_MMA(1, 1, At, B1); PG8_BAR; PG8_SCHED;
	s_sub_u32 s20, s0, s7
	s_subb_u32 s21, s1, 0
	s_add_u32 s20, s20, s4
	s_addc_u32 s21, s21, s5
	s_add_u32 s0, s64, s4
	s_addc_u32 s1, s65, s5
	s_add_i32 s19, s12, s78
	s_mov_b32 m0, s19
	ds_read_b128 v[192:195], v174 offset:49152
	ds_read_b128 v[196:199], v174 offset:50176
	ds_read_b128 v[200:203], v174 offset:51200
	ds_read_b128 v[204:207], v174 offset:52224
	ds_read_b128 v[208:211], v174 offset:53248
	ds_read_b128 v[212:215], v174 offset:54272
	ds_read_b128 v[216:219], v174 offset:55296
	ds_read_b128 v[220:223], v174 offset:56320
	global_load_lds_dwordx4 v152, s[0:1]
	s_add_i32 m0, s19, 0x2000
	s_add_i32 s19, s18, s78
	global_load_lds_dwordx4 v156, s[0:1]
	s_add_u32 s0, s0, s77
	s_addc_u32 s1, s1, 0
	s_mov_b32 m0, s19
	s_nop 0
	global_load_lds_dwordx4 v152, s[0:1]
	s_add_i32 m0, s19, 0x2000
	s_nop 0
	global_load_lds_dwordx4 v156, s[0:1]
	s_mov_b32 m0, s93
	s_nop 0
	global_load_lds_dwordx4 v150, s[20:21]
	s_mov_b32 m0, s94
	s_nop 0
	global_load_lds_dwordx4 v154, s[20:21]
	s_waitcnt vmcnt(8)
	s_waitcnt lgkmcnt(0)
	s_barrier
	s_setprio 1
	s_waitcnt lgkmcnt(0)
	v_mfma_f32_16x16x32_bf16 v[60:63], v[132:135], v[192:195], v[60:63]
	v_mfma_f32_16x16x32_bf16 v[56:59], v[142:145], v[192:195], v[56:59]
	v_mfma_f32_16x16x32_bf16 v[44:47], v[132:135], v[200:203], v[44:47]
	v_mfma_f32_16x16x32_bf16 v[40:43], v[142:145], v[200:203], v[40:43]
	v_mfma_f32_16x16x32_bf16 v[28:31], v[132:135], v[208:211], v[28:31]
	v_mfma_f32_16x16x32_bf16 v[24:27], v[142:145], v[208:211], v[24:27]
	v_mfma_f32_16x16x32_bf16 v[12:15], v[132:135], v[216:219], v[12:15]
	v_mfma_f32_16x16x32_bf16 v[8:11], v[142:145], v[216:219], v[8:11]
	v_mfma_f32_16x16x32_bf16 v[60:63], v[136:139], v[196:199], v[60:63]
	v_mfma_f32_16x16x32_bf16 v[56:59], v[158:161], v[196:199], v[56:59]
	v_mfma_f32_16x16x32_bf16 v[44:47], v[136:139], v[204:207], v[44:47]
	v_mfma_f32_16x16x32_bf16 v[40:43], v[158:161], v[204:207], v[40:43]
	v_mfma_f32_16x16x32_bf16 v[28:31], v[136:139], v[212:215], v[28:31]
	v_mfma_f32_16x16x32_bf16 v[24:27], v[158:161], v[212:215], v[24:27]
	v_mfma_f32_16x16x32_bf16 v[12:15], v[136:139], v[220:223], v[12:15]
	v_mfma_f32_16x16x32_bf16 v[8:11], v[158:161], v[220:223], v[8:11]
	s_setprio 0
	s_setprio 1
	v_mfma_f32_16x16x32_bf16 v[52:55], v[176:179], v[192:195], v[52:55]
	v_mfma_f32_16x16x32_bf16 v[48:51], v[184:187], v[192:195], v[48:51]
	v_mfma_f32_16x16x32_bf16 v[36:39], v[176:179], v[200:203], v[36:39]
	v_mfma_f32_16x16x32_bf16 v[32:35], v[184:187], v[200:203], v[32:35]
	v_mfma_f32_16x16x32_bf16 v[20:23], v[176:179], v[208:211], v[20:23]
	v_mfma_f32_16x16x32_bf16 v[16:19], v[184:187], v[208:211], v[16:19]
	v_mfma_f32_16x16x32_bf16 v[4:7], v[176:179], v[216:219], v[4:7]
	v_mfma_f32_16x16x32_bf16 v[0:3], v[184:187], v[216:219], v[0:3]
	v_mfma_f32_16x16x32_bf16 v[52:55], v[180:183], v[196:199], v[52:55]
	v_mfma_f32_16x16x32_bf16 v[48:51], v[188:191], v[196:199], v[48:51]
	v_mfma_f32_16x16x32_bf16 v[36:39], v[180:183], v[204:207], v[36:39]
	v_mfma_f32_16x16x32_bf16 v[32:35], v[188:191], v[204:207], v[32:35]
	v_mfma_f32_16x16x32_bf16 v[20:23], v[180:183], v[212:215], v[20:23]
	v_mfma_f32_16x16x32_bf16 v[16:19], v[188:191], v[212:215], v[16:19]
	v_mfma_f32_16x16x32_bf16 v[4:7], v[180:183], v[220:223], v[4:7]
	v_mfma_f32_16x16x32_bf16 v[0:3], v[188:191], v[220:223], v[0:3]
	s_setprio 0
	s_barrier
	s_add_i32 s38, s38, 2
	s_cmp_ge_u32 s38, s75
	s_cbranch_scc1 .LBB0_507

; DI void epilogue(const f32x4 (&acc)[2][2][4][2], int ph, unsigned char* ws, const float* pscale, const Unit& u, int wr, int wc, int fr, int fq) {
;     ...
;     if (mode == EP_BF16 || mode == EP_RELU2) {
;         const bool r2 = mode == EP_RELU2; const bool gateD = (ph == 0) && (u.pn * BM >= PC_G);
; #pragma unroll
;         for (int ai = 0; ai < 2; ++ai)
; #pragma unroll
;             for (int m = 0; m < 4; ++m) { u32x4 w[2];
; #pragma unroll
;                 for (int bj = 0; bj < 2; ++bj) { f32x4 v0 = acc[ai][bj][m][0], v1 = acc[ai][bj][m][1];
;                     if (gateD) {
; #pragma unroll
;                         for (int j = 0; j < 4; ++j) { v0[j] = 1.0f + __builtin_amdgcn_exp2f(-fmaxf(v0[j], -30.f) * LOG2E); v1[j] = 1.0f + __builtin_amdgcn_exp2f(-fmaxf(v1[j], -30.f) * LOG2E); } }
.LBB0_552:
	s_cmp_eq_u32 s67, 0
	s_cselect_b64 s[0:1], -1, 0
	s_cmp_gt_i32 s17, 17
	s_cselect_b64 s[18:19], -1, 0
	s_and_b64 s[18:19], s[0:1], s[18:19]
	s_andn2_b64 vcc, exec, s[18:19]
	s_cbranch_vccnz .Lep_nogate
	s_mov_b32 s18, 0xc1f00000
	s_mov_b32 s19, 0xbfb8aa3b
	v_max_f32_e32 v128, s18, v128
	v_max_f32_e32 v129, s18, v129
	v_max_f32_e32 v130, s18, v130
	v_max_f32_e32 v131, s18, v131
	v_mul_f32_e32 v128, s19, v128
	v_mul_f32_e32 v129, s19, v129
	v_mul_f32_e32 v130, s19, v130
	v_mul_f32_e32 v131, s19, v131
	v_exp_f32_e32 v128, v128
	v_exp_f32_e32 v129, v129
	v_exp_f32_e32 v130, v130
	v_exp_f32_e32 v131, v131
	v_max_f32_e32 v124, s18, v124
	v_max_f32_e32 v125, s18, v125
	v_max_f32_e32 v126, s18, v126
	v_max_f32_e32 v127, s18, v127
	v_mul_f32_e32 v124, s19, v124
	v_mul_f32_e32 v125, s19, v125
	v_mul_f32_e32 v126, s19, v126
	v_mul_f32_e32 v127, s19, v127
	v_exp_f32_e32 v124, v124
	v_exp_f32_e32 v125, v125
	v_exp_f32_e32 v126, v126
	v_exp_f32_e32 v127, v127
	v_pk_add_f32 v[128:129], v[128:129], 1.0 op_sel_hi:[1,0]
	v_pk_add_f32 v[130:131], v[130:131], 1.0 op_sel_hi:[1,0]
	v_max_f32_e32 v120, s18, v120
	v_max_f32_e32 v121, s18, v121
	v_max_f32_e32 v122, s18, v122
	v_max_f32_e32 v123, s18, v123
	v_mul_f32_e32 v120, s19, v120
	v_mul_f32_e32 v121, s19, v121
	v_mul_f32_e32 v122, s19, v122
	v_mul_f32_e32 v123, s19, v123
	v_exp_f32_e32 v120, v120
	v_exp_f32_e32 v121, v121
	v_exp_f32_e32 v122, v122
	v_exp_f32_e32 v123, v123
	v_pk_add_f32 v[124:125], v[124:125], 1.0 op_sel_hi:[1,0]
	v_pk_add_f32 v[126:127], v[126:127], 1.0 op_sel_hi:[1,0]
	v_max_f32_e32 v116, s18, v116
	v_max_f32_e32 v117, s18, v117
	v_max_f32_e32 v118, s18, v118
	v_max_f32_e32 v119, s18, v119
	v_mul_f32_e32 v116, s19, v116
	v_mul_f32_e32 v117, s19, v117
	v_mul_f32_e32 v118, s19, v118
	v_mul_f32_e32 v119, s19, v119
	v_exp_f32_e32 v116, v116
	v_exp_f32_e32 v117, v117
	v_exp_f32_e32 v118, v118
	v_exp_f32_e32 v119, v119
	v_pk_add_f32 v[120:121], v[120:121], 1.0 op_sel_hi:[1,0]
	v_pk_add_f32 v[122:123], v[122:123], 1.0 op_sel_hi:[1,0]
	v_max_f32_e32 v112, s18, v112
	v_max_f32_e32 v113, s18, v113
	v_max_f32_e32 v114, s18, v114
	v_max_f32_e32 v115, s18, v115
	v_mul_f32_e32 v112, s19, v112
	v_mul_f32_e32 v113, s19, v113
	v_mul_f32_e32 v114, s19, v114
	v_mul_f32_e32 v115, s19, v115
	v_exp_f32_e32 v112, v112
	v_exp_f32_e32 v113, v113
	v_exp_f32_e32 v114, v114
	v_exp_f32_e32 v115, v115
	v_pk_add_f32 v[116:117], v[116:117], 1.0 op_sel_hi:[1,0]
	v_pk_add_f32 v[118:119], v[118:119], 1.0 op_sel_hi:[1,0]
	v_max_f32_e32 v108, s18, v108
	v_max_f32_e32 v109, s18, v109
	v_max_f32_e32 v110, s18, v110
	v_max_f32_e32 v111, s18, v111
	v_mul_f32_e32 v108, s19, v108
	v_mul_f32_e32 v109, s19, v109
	v_mul_f32_e32 v110, s19, v110
	v_mul_f32_e32 v111, s19, v111
	v_exp_f32_e32 v108, v108
	v_exp_f32_e32 v109, v109
	v_exp_f32_e32 v110, v110
	v_exp_f32_e32 v111, v111
	v_pk_add_f32 v[112:113], v[112:113], 1.0 op_sel_hi:[1,0]
	v_pk_add_f32 v[114:115], v[114:115], 1.0 op_sel_hi:[1,0]
	v_max_f32_e32 v104, s18, v104
	v_max_f32_e32 v105, s18, v105
	v_max_f32_e32 v106, s18, v106
	v_max_f32_e32 v107, s18, v107
	v_mul_f32_e32 v104, s19, v104
	v_mul_f32_e32 v105, s19, v105
	v_mul_f32_e32 v106, s19, v106
	v_mul_f32_e32 v107, s19, v107
	v_exp_f32_e32 v104, v104
	v_exp_f32_e32 v105, v105
	v_exp_f32_e32 v106, v106
	v_exp_f32_e32 v107, v107
	v_pk_add_f32 v[108:109], v[108:109], 1.0 op_sel_hi:[1,0]
	v_pk_add_f32 v[110:111], v[110:111], 1.0 op_sel_hi:[1,0]
	v_max_f32_e32 v100, s18, v100
	v_max_f32_e32 v101, s18, v101
	v_max_f32_e32 v102, s18, v102
	v_max_f32_e32 v103, s18, v103
	v_mul_f32_e32 v100, s19, v100
	v_mul_f32_e32 v101, s19, v101
	v_mul_f32_e32 v102, s19, v102
	v_mul_f32_e32 v103, s19, v103
	v_exp_f32_e32 v100, v100
	v_exp_f32_e32 v101, v101
	v_exp_f32_e32 v102, v102
	v_exp_f32_e32 v103, v103
	v_pk_add_f32 v[104:105], v[104:105], 1.0 op_sel_hi:[1,0]
	v_pk_add_f32 v[106:107], v[106:107], 1.0 op_sel_hi:[1,0]
	v_max_f32_e32 v96, s18, v96
	v_max_f32_e32 v97, s18, v97
	v_max_f32_e32 v98, s18, v98
	v_max_f32_e32 v99, s18, v99
	v_mul_f32_e32 v96, s19, v96
	v_mul_f32_e32 v97, s19, v97
	v_mul_f32_e32 v98, s19, v98
	v_mul_f32_e32 v99, s19, v99
	v_exp_f32_e32 v96, v96
	v_exp_f32_e32 v97, v97
	v_exp_f32_e32 v98, v98
	v_exp_f32_e32 v99, v99
	v_pk_add_f32 v[100:101], v[100:101], 1.0 op_sel_hi:[1,0]
	v_pk_add_f32 v[102:103], v[102:103], 1.0 op_sel_hi:[1,0]
	v_max_f32_e32 v92, s18, v92
	v_max_f32_e32 v93, s18, v93
	v_max_f32_e32 v94, s18, v94
	v_max_f32_e32 v95, s18, v95
	v_mul_f32_e32 v92, s19, v92
	v_mul_f32_e32 v93, s19, v93
	v_mul_f32_e32 v94, s19, v94
	v_mul_f32_e32 v95, s19, v95
	v_exp_f32_e32 v92, v92
	v_exp_f32_e32 v93, v93
	v_exp_f32_e32 v94, v94
	v_exp_f32_e32 v95, v95
	v_pk_add_f32 v[96:97], v[96:97], 1.0 op_sel_hi:[1,0]
	v_pk_add_f32 v[98:99], v[98:99], 1.0 op_sel_hi:[1,0]
	v_max_f32_e32 v88, s18, v88
	v_max_f32_e32 v89, s18, v89
	v_max_f32_e32 v90, s18, v90
	v_max_f32_e32 v91, s18, v91
	v_mul_f32_e32 v88, s19, v88
	v_mul_f32_e32 v89, s19, v89
	v_mul_f32_e32 v90, s19, v90
	v_mul_f32_e32 v91, s19, v91
	v_exp_f32_e32 v88, v88
	v_exp_f32_e32 v89, v89
	v_exp_f32_e32 v90, v90
	v_exp_f32_e32 v91, v91
	v_pk_add_f32 v[92:93], v[92:93], 1.0 op_sel_hi:[1,0]
	v_pk_add_f32 v[94:95], v[94:95], 1.0 op_sel_hi:[1,0]
	v_max_f32_e32 v84, s18, v84
	v_max_f32_e32 v85, s18, v85
	v_max_f32_e32 v86, s18, v86
	v_max_f32_e32 v87, s18, v87
	v_mul_f32_e32 v84, s19, v84
	v_mul_f32_e32 v85, s19, v85
	v_mul_f32_e32 v86, s19, v86
	v_mul_f32_e32 v87, s19, v87
	v_exp_f32_e32 v84, v84
	v_exp_f32_e32 v85, v85
	v_exp_f32_e32 v86, v86
	v_exp_f32_e32 v87, v87
	v_pk_add_f32 v[88:89], v[88:89], 1.0 op_sel_hi:[1,0]
	v_pk_add_f32 v[90:91], v[90:91], 1.0 op_sel_hi:[1,0]
; DI void epilogue(const f32x4 (&acc)[2][2][4][2], int ph, unsigned char* ws, const float* pscale, const Unit& u, int wr, int wc, int fr, int fq) {
;     ...
;                 for (int bj = 0; bj < 2; ++bj) { f32x4 v0 = acc[ai][bj][m][0], v1 = acc[ai][bj][m][1];
;                     if (gateD) {
; #pragma unroll
;                         for (int j = 0; j < 4; ++j) { v0[j] = 1.0f + __builtin_amdgcn_exp2f(-fmaxf(v0[j], -30.f) * LOG2E); v1[j] = 1.0f + __builtin_amdgcn_exp2f(-fmaxf(v1[j], -30.f) * LOG2E); } }
	v_max_f32_e32 v76, s18, v76
	v_max_f32_e32 v77, s18, v77
	v_max_f32_e32 v78, s18, v78
	v_max_f32_e32 v79, s18, v79
	v_mul_f32_e32 v76, s19, v76
	v_mul_f32_e32 v77, s19, v77
	v_mul_f32_e32 v78, s19, v78
	v_mul_f32_e32 v79, s19, v79
	v_exp_f32_e32 v76, v76
	v_exp_f32_e32 v77, v77
	v_exp_f32_e32 v78, v78
	v_exp_f32_e32 v79, v79
	v_pk_add_f32 v[84:85], v[84:85], 1.0 op_sel_hi:[1,0]
	v_pk_add_f32 v[86:87], v[86:87], 1.0 op_sel_hi:[1,0]
	v_max_f32_e32 v72, s18, v72
	v_max_f32_e32 v73, s18, v73
	v_max_f32_e32 v74, s18, v74
	v_max_f32_e32 v75, s18, v75
	v_mul_f32_e32 v72, s19, v72
	v_mul_f32_e32 v73, s19, v73
	v_mul_f32_e32 v74, s19, v74
	v_mul_f32_e32 v75, s19, v75
	v_exp_f32_e32 v72, v72
	v_exp_f32_e32 v73, v73
	v_exp_f32_e32 v74, v74
	v_exp_f32_e32 v75, v75
	v_pk_add_f32 v[76:77], v[76:77], 1.0 op_sel_hi:[1,0]
	v_pk_add_f32 v[78:79], v[78:79], 1.0 op_sel_hi:[1,0]
	v_max_f32_e32 v68, s18, v68
	v_max_f32_e32 v69, s18, v69
	v_max_f32_e32 v70, s18, v70
	v_max_f32_e32 v71, s18, v71
	v_mul_f32_e32 v68, s19, v68
	v_mul_f32_e32 v69, s19, v69
	v_mul_f32_e32 v70, s19, v70
	v_mul_f32_e32 v71, s19, v71
	v_exp_f32_e32 v68, v68
	v_exp_f32_e32 v69, v69
	v_exp_f32_e32 v70, v70
	v_exp_f32_e32 v71, v71
	v_pk_add_f32 v[72:73], v[72:73], 1.0 op_sel_hi:[1,0]
	v_pk_add_f32 v[74:75], v[74:75], 1.0 op_sel_hi:[1,0]
	v_max_f32_e32 v64, s18, v64
	v_max_f32_e32 v65, s18, v65
	v_max_f32_e32 v66, s18, v66
	v_max_f32_e32 v67, s18, v67
	v_mul_f32_e32 v64, s19, v64
	v_mul_f32_e32 v65, s19, v65
	v_mul_f32_e32 v66, s19, v66
	v_mul_f32_e32 v67, s19, v67
	v_exp_f32_e32 v64, v64
	v_exp_f32_e32 v65, v65
	v_exp_f32_e32 v66, v66
	v_exp_f32_e32 v67, v67
	v_pk_add_f32 v[68:69], v[68:69], 1.0 op_sel_hi:[1,0]
	v_pk_add_f32 v[70:71], v[70:71], 1.0 op_sel_hi:[1,0]
	v_max_f32_e32 v60, s18, v60
	v_max_f32_e32 v61, s18, v61
	v_max_f32_e32 v62, s18, v62
	v_max_f32_e32 v63, s18, v63
	v_mul_f32_e32 v60, s19, v60
	v_mul_f32_e32 v61, s19, v61
	v_mul_f32_e32 v62, s19, v62
	v_mul_f32_e32 v63, s19, v63
	v_exp_f32_e32 v60, v60
	v_exp_f32_e32 v61, v61
	v_exp_f32_e32 v62, v62
	v_exp_f32_e32 v63, v63
	v_pk_add_f32 v[64:65], v[64:65], 1.0 op_sel_hi:[1,0]
	v_pk_add_f32 v[66:67], v[66:67], 1.0 op_sel_hi:[1,0]
	v_max_f32_e32 v56, s18, v56
	v_max_f32_e32 v57, s18, v57
	v_max_f32_e32 v58, s18, v58
	v_max_f32_e32 v59, s18, v59
	v_mul_f32_e32 v56, s19, v56
	v_mul_f32_e32 v57, s19, v57
	v_mul_f32_e32 v58, s19, v58
	v_mul_f32_e32 v59, s19, v59
	v_exp_f32_e32 v56, v56
	v_exp_f32_e32 v57, v57
	v_exp_f32_e32 v58, v58
	v_exp_f32_e32 v59, v59
	v_pk_add_f32 v[60:61], v[60:61], 1.0 op_sel_hi:[1,0]
	v_pk_add_f32 v[62:63], v[62:63], 1.0 op_sel_hi:[1,0]
	v_max_f32_e32 v52, s18, v52
	v_max_f32_e32 v53, s18, v53
	v_max_f32_e32 v54, s18, v54
	v_max_f32_e32 v55, s18, v55
	v_mul_f32_e32 v52, s19, v52
	v_mul_f32_e32 v53, s19, v53
	v_mul_f32_e32 v54, s19, v54
	v_mul_f32_e32 v55, s19, v55
	v_exp_f32_e32 v52, v52
	v_exp_f32_e32 v53, v53
	v_exp_f32_e32 v54, v54
	v_exp_f32_e32 v55, v55
	v_pk_add_f32 v[56:57], v[56:57], 1.0 op_sel_hi:[1,0]
	v_pk_add_f32 v[58:59], v[58:59], 1.0 op_sel_hi:[1,0]
	v_max_f32_e32 v48, s18, v48
	v_max_f32_e32 v49, s18, v49
	v_max_f32_e32 v50, s18, v50
	v_max_f32_e32 v51, s18, v51
	v_mul_f32_e32 v48, s19, v48
	v_mul_f32_e32 v49, s19, v49
	v_mul_f32_e32 v50, s19, v50
	v_mul_f32_e32 v51, s19, v51
	v_exp_f32_e32 v48, v48
	v_exp_f32_e32 v49, v49
	v_exp_f32_e32 v50, v50
	v_exp_f32_e32 v51, v51
	v_pk_add_f32 v[52:53], v[52:53], 1.0 op_sel_hi:[1,0]
	v_pk_add_f32 v[54:55], v[54:55], 1.0 op_sel_hi:[1,0]
	v_max_f32_e32 v44, s18, v44
	v_max_f32_e32 v45, s18, v45
	v_max_f32_e32 v46, s18, v46
	v_max_f32_e32 v47, s18, v47
	v_mul_f32_e32 v44, s19, v44
	v_mul_f32_e32 v45, s19, v45
	v_mul_f32_e32 v46, s19, v46
	v_mul_f32_e32 v47, s19, v47
	v_exp_f32_e32 v44, v44
	v_exp_f32_e32 v45, v45
	v_exp_f32_e32 v46, v46
	v_exp_f32_e32 v47, v47
	v_pk_add_f32 v[48:49], v[48:49], 1.0 op_sel_hi:[1,0]
	v_pk_add_f32 v[50:51], v[50:51], 1.0 op_sel_hi:[1,0]
	v_max_f32_e32 v40, s18, v40
	v_max_f32_e32 v41, s18, v41
	v_max_f32_e32 v42, s18, v42
	v_max_f32_e32 v43, s18, v43
	v_mul_f32_e32 v40, s19, v40
	v_mul_f32_e32 v41, s19, v41
	v_mul_f32_e32 v42, s19, v42
	v_mul_f32_e32 v43, s19, v43
	v_exp_f32_e32 v40, v40
	v_exp_f32_e32 v41, v41
	v_exp_f32_e32 v42, v42
	v_exp_f32_e32 v43, v43
	v_pk_add_f32 v[44:45], v[44:45], 1.0 op_sel_hi:[1,0]
	v_pk_add_f32 v[46:47], v[46:47], 1.0 op_sel_hi:[1,0]
	v_max_f32_e32 v36, s18, v36
	v_max_f32_e32 v37, s18, v37
	v_max_f32_e32 v38, s18, v38
	v_max_f32_e32 v39, s18, v39
	v_mul_f32_e32 v36, s19, v36
	v_mul_f32_e32 v37, s19, v37
	v_mul_f32_e32 v38, s19, v38
	v_mul_f32_e32 v39, s19, v39
	v_exp_f32_e32 v36, v36
	v_exp_f32_e32 v37, v37
	v_exp_f32_e32 v38, v38
	v_exp_f32_e32 v39, v39
	v_pk_add_f32 v[40:41], v[40:41], 1.0 op_sel_hi:[1,0]
	v_pk_add_f32 v[42:43], v[42:43], 1.0 op_sel_hi:[1,0]
	v_max_f32_e32 v32, s18, v32
	v_max_f32_e32 v33, s18, v33
	v_max_f32_e32 v34, s18, v34
	v_max_f32_e32 v35, s18, v35
	v_mul_f32_e32 v32, s19, v32
	v_mul_f32_e32 v33, s19, v33
	v_mul_f32_e32 v34, s19, v34
	v_mul_f32_e32 v35, s19, v35
	v_exp_f32_e32 v32, v32
	v_exp_f32_e32 v33, v33
	v_exp_f32_e32 v34, v34
	v_exp_f32_e32 v35, v35
	v_pk_add_f32 v[36:37], v[36:37], 1.0 op_sel_hi:[1,0]
	v_pk_add_f32 v[38:39], v[38:39], 1.0 op_sel_hi:[1,0]
	v_max_f32_e32 v28, s18, v28
	v_max_f32_e32 v29, s18, v29
	v_max_f32_e32 v30, s18, v30
	v_max_f32_e32 v31, s18, v31
	v_mul_f32_e32 v28, s19, v28
	v_mul_f32_e32 v29, s19, v29
	v_mul_f32_e32 v30, s19, v30
	v_mul_f32_e32 v31, s19, v31
	v_exp_f32_e32 v28, v28
	v_exp_f32_e32 v29, v29
	v_exp_f32_e32 v30, v30
	v_exp_f32_e32 v31, v31
	v_pk_add_f32 v[32:33], v[32:33], 1.0 op_sel_hi:[1,0]
; DI void epilogue(const f32x4 (&acc)[2][2][4][2], int ph, unsigned char* ws, const float* pscale, const Unit& u, int wr, int wc, int fr, int fq) {
;     ...
;                         for (int j = 0; j < 4; ++j) { v0[j] = 1.0f + __builtin_amdgcn_exp2f(-fmaxf(v0[j], -30.f) * LOG2E); v1[j] = 1.0f + __builtin_amdgcn_exp2f(-fmaxf(v1[j], -30.f) * LOG2E); } }
;                     if (r2) {
; #pragma unroll
;                         for (int j = 0; j < 4; ++j) { const float a = fmaxf(v0[j], 0.f), b = fmaxf(v1[j], 0.f); v0[j] = a * a; v1[j] = b * b; } }
	v_pk_add_f32 v[34:35], v[34:35], 1.0 op_sel_hi:[1,0]
	v_max_f32_e32 v24, s18, v24
	v_max_f32_e32 v25, s18, v25
	v_max_f32_e32 v26, s18, v26
	v_max_f32_e32 v27, s18, v27
	v_mul_f32_e32 v24, s19, v24
	v_mul_f32_e32 v25, s19, v25
	v_mul_f32_e32 v26, s19, v26
	v_mul_f32_e32 v27, s19, v27
	v_exp_f32_e32 v24, v24
	v_exp_f32_e32 v25, v25
	v_exp_f32_e32 v26, v26
	v_exp_f32_e32 v27, v27
	v_pk_add_f32 v[28:29], v[28:29], 1.0 op_sel_hi:[1,0]
	v_pk_add_f32 v[30:31], v[30:31], 1.0 op_sel_hi:[1,0]
	v_max_f32_e32 v20, s18, v20
	v_max_f32_e32 v21, s18, v21
	v_max_f32_e32 v22, s18, v22
	v_max_f32_e32 v23, s18, v23
	v_mul_f32_e32 v20, s19, v20
	v_mul_f32_e32 v21, s19, v21
	v_mul_f32_e32 v22, s19, v22
	v_mul_f32_e32 v23, s19, v23
	v_exp_f32_e32 v20, v20
	v_exp_f32_e32 v21, v21
	v_exp_f32_e32 v22, v22
	v_exp_f32_e32 v23, v23
	v_pk_add_f32 v[24:25], v[24:25], 1.0 op_sel_hi:[1,0]
	v_pk_add_f32 v[26:27], v[26:27], 1.0 op_sel_hi:[1,0]
	v_max_f32_e32 v16, s18, v16
	v_max_f32_e32 v17, s18, v17
	v_max_f32_e32 v18, s18, v18
	v_max_f32_e32 v19, s18, v19
	v_mul_f32_e32 v16, s19, v16
	v_mul_f32_e32 v17, s19, v17
	v_mul_f32_e32 v18, s19, v18
	v_mul_f32_e32 v19, s19, v19
	v_exp_f32_e32 v16, v16
	v_exp_f32_e32 v17, v17
	v_exp_f32_e32 v18, v18
	v_exp_f32_e32 v19, v19
	v_pk_add_f32 v[20:21], v[20:21], 1.0 op_sel_hi:[1,0]
	v_pk_add_f32 v[22:23], v[22:23], 1.0 op_sel_hi:[1,0]
	v_max_f32_e32 v12, s18, v12
	v_max_f32_e32 v13, s18, v13
	v_max_f32_e32 v14, s18, v14
	v_max_f32_e32 v15, s18, v15
	v_mul_f32_e32 v12, s19, v12
	v_mul_f32_e32 v13, s19, v13
	v_mul_f32_e32 v14, s19, v14
	v_mul_f32_e32 v15, s19, v15
	v_exp_f32_e32 v12, v12
	v_exp_f32_e32 v13, v13
	v_exp_f32_e32 v14, v14
	v_exp_f32_e32 v15, v15
	v_pk_add_f32 v[16:17], v[16:17], 1.0 op_sel_hi:[1,0]
	v_pk_add_f32 v[18:19], v[18:19], 1.0 op_sel_hi:[1,0]
	v_max_f32_e32 v8, s18, v8
	v_max_f32_e32 v9, s18, v9
	v_max_f32_e32 v10, s18, v10
	v_max_f32_e32 v11, s18, v11
	v_mul_f32_e32 v8, s19, v8
	v_mul_f32_e32 v9, s19, v9
	v_mul_f32_e32 v10, s19, v10
	v_mul_f32_e32 v11, s19, v11
	v_exp_f32_e32 v8, v8
	v_exp_f32_e32 v9, v9
	v_exp_f32_e32 v10, v10
	v_exp_f32_e32 v11, v11
	v_pk_add_f32 v[12:13], v[12:13], 1.0 op_sel_hi:[1,0]
	v_pk_add_f32 v[14:15], v[14:15], 1.0 op_sel_hi:[1,0]
	v_max_f32_e32 v4, s18, v4
	v_max_f32_e32 v5, s18, v5
	v_max_f32_e32 v6, s18, v6
	v_max_f32_e32 v7, s18, v7
	v_mul_f32_e32 v4, s19, v4
	v_mul_f32_e32 v5, s19, v5
	v_mul_f32_e32 v6, s19, v6
	v_mul_f32_e32 v7, s19, v7
	v_exp_f32_e32 v4, v4
	v_exp_f32_e32 v5, v5
	v_exp_f32_e32 v6, v6
	v_exp_f32_e32 v7, v7
	v_pk_add_f32 v[8:9], v[8:9], 1.0 op_sel_hi:[1,0]
	v_pk_add_f32 v[10:11], v[10:11], 1.0 op_sel_hi:[1,0]
	v_max_f32_e32 v0, s18, v0
	v_max_f32_e32 v1, s18, v1
	v_max_f32_e32 v2, s18, v2
	v_max_f32_e32 v3, s18, v3
	v_mul_f32_e32 v0, s19, v0
	v_mul_f32_e32 v1, s19, v1
	v_mul_f32_e32 v2, s19, v2
	v_mul_f32_e32 v3, s19, v3
	v_exp_f32_e32 v0, v0
	v_exp_f32_e32 v1, v1
	v_exp_f32_e32 v2, v2
	v_exp_f32_e32 v3, v3
	v_pk_add_f32 v[4:5], v[4:5], 1.0 op_sel_hi:[1,0]
	v_pk_add_f32 v[6:7], v[6:7], 1.0 op_sel_hi:[1,0]
	s_nop 0
	v_pk_add_f32 v[0:1], v[0:1], 1.0 op_sel_hi:[1,0]
	v_pk_add_f32 v[2:3], v[2:3], 1.0 op_sel_hi:[1,0]
.Lep_nogate:
	s_cmp_lg_u32 s68, 1
	s_cbranch_scc1 .Lep_norelu
	v_max_f32_e32 v128, 0, v128
	v_max_f32_e32 v129, 0, v129
	v_max_f32_e32 v130, 0, v130
	v_max_f32_e32 v131, 0, v131
	v_pk_mul_f32 v[128:129], v[128:129], v[128:129]
	v_pk_mul_f32 v[130:131], v[130:131], v[130:131]
	v_max_f32_e32 v124, 0, v124
	v_max_f32_e32 v125, 0, v125
	v_max_f32_e32 v126, 0, v126
	v_max_f32_e32 v127, 0, v127
	v_pk_mul_f32 v[124:125], v[124:125], v[124:125]
	v_pk_mul_f32 v[126:127], v[126:127], v[126:127]
	v_max_f32_e32 v120, 0, v120
	v_max_f32_e32 v121, 0, v121
	v_max_f32_e32 v122, 0, v122
	v_max_f32_e32 v123, 0, v123
	v_pk_mul_f32 v[120:121], v[120:121], v[120:121]
	v_pk_mul_f32 v[122:123], v[122:123], v[122:123]
	v_max_f32_e32 v116, 0, v116
	v_max_f32_e32 v117, 0, v117
	v_max_f32_e32 v118, 0, v118
	v_max_f32_e32 v119, 0, v119
	v_pk_mul_f32 v[116:117], v[116:117], v[116:117]
	v_pk_mul_f32 v[118:119], v[118:119], v[118:119]
	v_max_f32_e32 v112, 0, v112
	v_max_f32_e32 v113, 0, v113
	v_max_f32_e32 v114, 0, v114
	v_max_f32_e32 v115, 0, v115
	v_pk_mul_f32 v[112:113], v[112:113], v[112:113]
	v_pk_mul_f32 v[114:115], v[114:115], v[114:115]
	v_max_f32_e32 v108, 0, v108
	v_max_f32_e32 v109, 0, v109
	v_max_f32_e32 v110, 0, v110
	v_max_f32_e32 v111, 0, v111
	v_pk_mul_f32 v[108:109], v[108:109], v[108:109]
	v_pk_mul_f32 v[110:111], v[110:111], v[110:111]
	v_max_f32_e32 v104, 0, v104
	v_max_f32_e32 v105, 0, v105
	v_max_f32_e32 v106, 0, v106
	v_max_f32_e32 v107, 0, v107
	v_pk_mul_f32 v[104:105], v[104:105], v[104:105]
	v_pk_mul_f32 v[106:107], v[106:107], v[106:107]
	v_max_f32_e32 v100, 0, v100
	v_max_f32_e32 v101, 0, v101
	v_max_f32_e32 v102, 0, v102
	v_max_f32_e32 v103, 0, v103
	v_pk_mul_f32 v[100:101], v[100:101], v[100:101]
	v_pk_mul_f32 v[102:103], v[102:103], v[102:103]
	v_max_f32_e32 v96, 0, v96
	v_max_f32_e32 v97, 0, v97
	v_max_f32_e32 v98, 0, v98
	v_max_f32_e32 v99, 0, v99
	v_pk_mul_f32 v[96:97], v[96:97], v[96:97]
	v_pk_mul_f32 v[98:99], v[98:99], v[98:99]
	v_max_f32_e32 v92, 0, v92
	v_max_f32_e32 v93, 0, v93
	v_max_f32_e32 v94, 0, v94
	v_max_f32_e32 v95, 0, v95
	v_pk_mul_f32 v[92:93], v[92:93], v[92:93]
	v_pk_mul_f32 v[94:95], v[94:95], v[94:95]
	v_max_f32_e32 v88, 0, v88
	v_max_f32_e32 v89, 0, v89
	v_max_f32_e32 v90, 0, v90
	v_max_f32_e32 v91, 0, v91
	v_pk_mul_f32 v[88:89], v[88:89], v[88:89]
	v_pk_mul_f32 v[90:91], v[90:91], v[90:91]
	v_max_f32_e32 v84, 0, v84
	v_max_f32_e32 v85, 0, v85
	v_max_f32_e32 v86, 0, v86
	v_max_f32_e32 v87, 0, v87
	v_pk_mul_f32 v[84:85], v[84:85], v[84:85]
; DI unsigned pk2(float lo, float hi) { f32x2 v = {lo, hi}; bf16x2_t b = __builtin_convertvector(v, bf16x2_t); return __builtin_bit_cast(unsigned, b); }
; DI unsigned ror8(unsigned x) { return (unsigned)__builtin_amdgcn_mov_dpp((int)x, 0x128, 0xf, 0xf, true); }
; DI void store_lines(bf16_t* Ob, size_t row, int ldc, int colw, int fr, int fq, const u32x4& w0, const u32x4& w1) {
;     const bool lo = (fr & 8) == 0;
;     const u32x4 snd = lo ? w1 : w0;
;     u32x4 rcv; rcv.x = ror8(snd.x); rcv.y = ror8(snd.y); rcv.z = ror8(snd.z); rcv.w = ror8(snd.w);
;     const u32x4 dA = lo ? w0 : rcv, dB = lo ? rcv : w1;
;     const int col = colw + 8 * fq + (lo ? 0 : 32);
;     __builtin_nontemporal_store(dA, (u32x4*)(Ob + (lo ? row : row - 8) * ldc + col));
;     __builtin_nontemporal_store(dB, (u32x4*)(Ob + (lo ? row + 8 : row) * ldc + col));
; }
; DI void epilogue(const f32x4 (&acc)[2][2][4][2], int ph, unsigned char* ws, const float* pscale, const Unit& u, int wr, int wc, int fr, int fq) {
;     ...
;                         for (int j = 0; j < 4; ++j) { const float a = fmaxf(v0[j], 0.f), b = fmaxf(v1[j], 0.f); v0[j] = a * a; v1[j] = b * b; } }
;                     w[bj].x = pk2(v0[0], v0[1]); w[bj].y = pk2(v0[2], v0[3]); w[bj].z = pk2(v1[0], v1[1]); w[bj].w = pk2(v1[2], v1[3]); }
;                 store_lines(Ob, (size_t)(row0 + ai * HALF + m * 16), ldc, colw, fr, fq, w[0], w[1]); }
	v_pk_mul_f32 v[86:87], v[86:87], v[86:87]
	v_max_f32_e32 v76, 0, v76
	v_max_f32_e32 v77, 0, v77
	v_max_f32_e32 v78, 0, v78
	v_max_f32_e32 v79, 0, v79
	v_pk_mul_f32 v[76:77], v[76:77], v[76:77]
	v_pk_mul_f32 v[78:79], v[78:79], v[78:79]
	v_max_f32_e32 v72, 0, v72
	v_max_f32_e32 v73, 0, v73
	v_max_f32_e32 v74, 0, v74
	v_max_f32_e32 v75, 0, v75
	v_pk_mul_f32 v[72:73], v[72:73], v[72:73]
	v_pk_mul_f32 v[74:75], v[74:75], v[74:75]
	v_max_f32_e32 v68, 0, v68
	v_max_f32_e32 v69, 0, v69
	v_max_f32_e32 v70, 0, v70
	v_max_f32_e32 v71, 0, v71
	v_pk_mul_f32 v[68:69], v[68:69], v[68:69]
	v_pk_mul_f32 v[70:71], v[70:71], v[70:71]
	v_max_f32_e32 v64, 0, v64
	v_max_f32_e32 v65, 0, v65
	v_max_f32_e32 v66, 0, v66
	v_max_f32_e32 v67, 0, v67
	v_pk_mul_f32 v[64:65], v[64:65], v[64:65]
	v_pk_mul_f32 v[66:67], v[66:67], v[66:67]
	v_max_f32_e32 v60, 0, v60
	v_max_f32_e32 v61, 0, v61
	v_max_f32_e32 v62, 0, v62
	v_max_f32_e32 v63, 0, v63
	v_pk_mul_f32 v[60:61], v[60:61], v[60:61]
	v_pk_mul_f32 v[62:63], v[62:63], v[62:63]
	v_max_f32_e32 v56, 0, v56
	v_max_f32_e32 v57, 0, v57
	v_max_f32_e32 v58, 0, v58
	v_max_f32_e32 v59, 0, v59
	v_pk_mul_f32 v[56:57], v[56:57], v[56:57]
	v_pk_mul_f32 v[58:59], v[58:59], v[58:59]
	v_max_f32_e32 v52, 0, v52
	v_max_f32_e32 v53, 0, v53
	v_max_f32_e32 v54, 0, v54
	v_max_f32_e32 v55, 0, v55
	v_pk_mul_f32 v[52:53], v[52:53], v[52:53]
	v_pk_mul_f32 v[54:55], v[54:55], v[54:55]
	v_max_f32_e32 v48, 0, v48
	v_max_f32_e32 v49, 0, v49
	v_max_f32_e32 v50, 0, v50
	v_max_f32_e32 v51, 0, v51
	v_pk_mul_f32 v[48:49], v[48:49], v[48:49]
	v_pk_mul_f32 v[50:51], v[50:51], v[50:51]
	v_max_f32_e32 v44, 0, v44
	v_max_f32_e32 v45, 0, v45
	v_max_f32_e32 v46, 0, v46
	v_max_f32_e32 v47, 0, v47
	v_pk_mul_f32 v[44:45], v[44:45], v[44:45]
	v_pk_mul_f32 v[46:47], v[46:47], v[46:47]
	v_max_f32_e32 v40, 0, v40
	v_max_f32_e32 v41, 0, v41
	v_max_f32_e32 v42, 0, v42
	v_max_f32_e32 v43, 0, v43
	v_pk_mul_f32 v[40:41], v[40:41], v[40:41]
	v_pk_mul_f32 v[42:43], v[42:43], v[42:43]
	v_max_f32_e32 v36, 0, v36
	v_max_f32_e32 v37, 0, v37
	v_max_f32_e32 v38, 0, v38
	v_max_f32_e32 v39, 0, v39
	v_pk_mul_f32 v[36:37], v[36:37], v[36:37]
	v_pk_mul_f32 v[38:39], v[38:39], v[38:39]
	v_max_f32_e32 v32, 0, v32
	v_max_f32_e32 v33, 0, v33
	v_max_f32_e32 v34, 0, v34
	v_max_f32_e32 v35, 0, v35
	v_pk_mul_f32 v[32:33], v[32:33], v[32:33]
	v_pk_mul_f32 v[34:35], v[34:35], v[34:35]
	v_max_f32_e32 v28, 0, v28
	v_max_f32_e32 v29, 0, v29
	v_max_f32_e32 v30, 0, v30
	v_max_f32_e32 v31, 0, v31
	v_pk_mul_f32 v[28:29], v[28:29], v[28:29]
	v_pk_mul_f32 v[30:31], v[30:31], v[30:31]
	v_max_f32_e32 v24, 0, v24
	v_max_f32_e32 v25, 0, v25
	v_max_f32_e32 v26, 0, v26
	v_max_f32_e32 v27, 0, v27
	v_pk_mul_f32 v[24:25], v[24:25], v[24:25]
	v_pk_mul_f32 v[26:27], v[26:27], v[26:27]
	v_max_f32_e32 v20, 0, v20
	v_max_f32_e32 v21, 0, v21
	v_max_f32_e32 v22, 0, v22
	v_max_f32_e32 v23, 0, v23
	v_pk_mul_f32 v[20:21], v[20:21], v[20:21]
	v_pk_mul_f32 v[22:23], v[22:23], v[22:23]
	v_max_f32_e32 v16, 0, v16
	v_max_f32_e32 v17, 0, v17
	v_max_f32_e32 v18, 0, v18
	v_max_f32_e32 v19, 0, v19
	v_pk_mul_f32 v[16:17], v[16:17], v[16:17]
	v_pk_mul_f32 v[18:19], v[18:19], v[18:19]
	v_max_f32_e32 v12, 0, v12
	v_max_f32_e32 v13, 0, v13
	v_max_f32_e32 v14, 0, v14
	v_max_f32_e32 v15, 0, v15
	v_pk_mul_f32 v[12:13], v[12:13], v[12:13]
	v_pk_mul_f32 v[14:15], v[14:15], v[14:15]
	v_max_f32_e32 v8, 0, v8
	v_max_f32_e32 v9, 0, v9
	v_max_f32_e32 v10, 0, v10
	v_max_f32_e32 v11, 0, v11
	v_pk_mul_f32 v[8:9], v[8:9], v[8:9]
	v_pk_mul_f32 v[10:11], v[10:11], v[10:11]
	v_max_f32_e32 v4, 0, v4
	v_max_f32_e32 v5, 0, v5
	v_max_f32_e32 v6, 0, v6
	v_max_f32_e32 v7, 0, v7
	v_pk_mul_f32 v[4:5], v[4:5], v[4:5]
	v_pk_mul_f32 v[6:7], v[6:7], v[6:7]
	v_max_f32_e32 v0, 0, v0
	v_max_f32_e32 v1, 0, v1
	v_max_f32_e32 v2, 0, v2
	v_max_f32_e32 v3, 0, v3
	v_pk_mul_f32 v[0:1], v[0:1], v[0:1]
	v_pk_mul_f32 v[2:3], v[2:3], v[2:3]
.Lep_norelu:
	v_and_b32_e32 v83, 8, v80
	v_sub_u32_e32 v175, v82, v83
	v_lshlrev_b32_e32 v83, 2, v83
	v_or3_b32 v132, v83, s66, v172
	v_ashrrev_i32_e32 v133, 31, v132
	v_lshl_add_u64 v[136:137], v[132:133], 1, s[40:41]
	v_mad_u64_u32 v[146:147], s[0:1], s64, v175, 0
	s_lshl_b32 s38, s64, 4
	s_mov_b32 s39, 0
	s_lshl_b32 s42, s64, 7
	s_mov_b32 s43, 0
	v_lshl_add_u64 v[146:147], v[146:147], 1, v[136:137]
	v_cvt_pk_bf16_f32 v128, v128, v129
	v_cvt_pk_bf16_f32 v129, v130, v131
	v_cvt_pk_bf16_f32 v130, v124, v125
	v_cvt_pk_bf16_f32 v131, v126, v127
	v_cvt_pk_bf16_f32 v120, v120, v121
	v_cvt_pk_bf16_f32 v121, v122, v123
	v_cvt_pk_bf16_f32 v122, v116, v117
	v_cvt_pk_bf16_f32 v123, v118, v119
	v_mov_b32_e32 v132, v128
	v_mov_b32_e32 v133, v129
	v_mov_b32_e32 v134, v130
	v_mov_b32_e32 v135, v131
	v_mov_b32_dpp v128, v120 row_ror:8 row_mask:0xf bank_mask:0xc
	v_mov_b32_dpp v129, v121 row_ror:8 row_mask:0xf bank_mask:0xc
	v_mov_b32_dpp v130, v122 row_ror:8 row_mask:0xf bank_mask:0xc
	v_mov_b32_dpp v131, v123 row_ror:8 row_mask:0xf bank_mask:0xc
	v_mov_b32_dpp v120, v132 row_ror:8 row_mask:0xf bank_mask:0x3
	v_mov_b32_dpp v121, v133 row_ror:8 row_mask:0xf bank_mask:0x3
	v_mov_b32_dpp v122, v134 row_ror:8 row_mask:0xf bank_mask:0x3
	v_mov_b32_dpp v123, v135 row_ror:8 row_mask:0xf bank_mask:0x3
	global_store_dwordx4 v[146:147], v[128:131], off nt
	v_lshl_add_u64 v[146:147], v[146:147], 0, s[38:39]
	global_store_dwordx4 v[146:147], v[120:123], off nt
	v_lshl_add_u64 v[146:147], v[146:147], 0, s[38:39]
	v_cvt_pk_bf16_f32 v112, v112, v113
	v_cvt_pk_bf16_f32 v113, v114, v115
	v_cvt_pk_bf16_f32 v114, v108, v109
	v_cvt_pk_bf16_f32 v115, v110, v111
	v_cvt_pk_bf16_f32 v104, v104, v105
	v_cvt_pk_bf16_f32 v105, v106, v107
	v_cvt_pk_bf16_f32 v106, v100, v101
; DI unsigned pk2(float lo, float hi) { f32x2 v = {lo, hi}; bf16x2_t b = __builtin_convertvector(v, bf16x2_t); return __builtin_bit_cast(unsigned, b); }
; DI unsigned ror8(unsigned x) { return (unsigned)__builtin_amdgcn_mov_dpp((int)x, 0x128, 0xf, 0xf, true); }
; DI void store_lines(bf16_t* Ob, size_t row, int ldc, int colw, int fr, int fq, const u32x4& w0, const u32x4& w1) {
;     const bool lo = (fr & 8) == 0;
;     const u32x4 snd = lo ? w1 : w0;
;     u32x4 rcv; rcv.x = ror8(snd.x); rcv.y = ror8(snd.y); rcv.z = ror8(snd.z); rcv.w = ror8(snd.w);
;     const u32x4 dA = lo ? w0 : rcv, dB = lo ? rcv : w1;
;     const int col = colw + 8 * fq + (lo ? 0 : 32);
;     __builtin_nontemporal_store(dA, (u32x4*)(Ob + (lo ? row : row - 8) * ldc + col));
;     __builtin_nontemporal_store(dB, (u32x4*)(Ob + (lo ? row + 8 : row) * ldc + col));
; }
; DI void epilogue(const f32x4 (&acc)[2][2][4][2], int ph, unsigned char* ws, const float* pscale, const Unit& u, int wr, int wc, int fr, int fq) {
;     ...
;                     w[bj].x = pk2(v0[0], v0[1]); w[bj].y = pk2(v0[2], v0[3]); w[bj].z = pk2(v1[0], v1[1]); w[bj].w = pk2(v1[2], v1[3]); }
;                 store_lines(Ob, (size_t)(row0 + ai * HALF + m * 16), ldc, colw, fr, fq, w[0], w[1]); }
	v_cvt_pk_bf16_f32 v107, v102, v103
	v_mov_b32_e32 v132, v112
	v_mov_b32_e32 v133, v113
	v_mov_b32_e32 v134, v114
	v_mov_b32_e32 v135, v115
	v_mov_b32_dpp v112, v104 row_ror:8 row_mask:0xf bank_mask:0xc
	v_mov_b32_dpp v113, v105 row_ror:8 row_mask:0xf bank_mask:0xc
	v_mov_b32_dpp v114, v106 row_ror:8 row_mask:0xf bank_mask:0xc
	v_mov_b32_dpp v115, v107 row_ror:8 row_mask:0xf bank_mask:0xc
	v_mov_b32_dpp v104, v132 row_ror:8 row_mask:0xf bank_mask:0x3
	v_mov_b32_dpp v105, v133 row_ror:8 row_mask:0xf bank_mask:0x3
	v_mov_b32_dpp v106, v134 row_ror:8 row_mask:0xf bank_mask:0x3
	v_mov_b32_dpp v107, v135 row_ror:8 row_mask:0xf bank_mask:0x3
	global_store_dwordx4 v[146:147], v[112:115], off nt
	v_lshl_add_u64 v[146:147], v[146:147], 0, s[38:39]
	global_store_dwordx4 v[146:147], v[104:107], off nt
	v_lshl_add_u64 v[146:147], v[146:147], 0, s[38:39]
	v_cvt_pk_bf16_f32 v96, v96, v97
	v_cvt_pk_bf16_f32 v97, v98, v99
	v_cvt_pk_bf16_f32 v98, v92, v93
	v_cvt_pk_bf16_f32 v99, v94, v95
	v_cvt_pk_bf16_f32 v88, v88, v89
	v_cvt_pk_bf16_f32 v89, v90, v91
	v_cvt_pk_bf16_f32 v90, v84, v85
	v_cvt_pk_bf16_f32 v91, v86, v87
	v_mov_b32_e32 v132, v96
	v_mov_b32_e32 v133, v97
	v_mov_b32_e32 v134, v98
	v_mov_b32_e32 v135, v99
	v_mov_b32_dpp v96, v88 row_ror:8 row_mask:0xf bank_mask:0xc
	v_mov_b32_dpp v97, v89 row_ror:8 row_mask:0xf bank_mask:0xc
	v_mov_b32_dpp v98, v90 row_ror:8 row_mask:0xf bank_mask:0xc
	v_mov_b32_dpp v99, v91 row_ror:8 row_mask:0xf bank_mask:0xc
	v_mov_b32_dpp v88, v132 row_ror:8 row_mask:0xf bank_mask:0x3
	v_mov_b32_dpp v89, v133 row_ror:8 row_mask:0xf bank_mask:0x3
	v_mov_b32_dpp v90, v134 row_ror:8 row_mask:0xf bank_mask:0x3
	v_mov_b32_dpp v91, v135 row_ror:8 row_mask:0xf bank_mask:0x3
	global_store_dwordx4 v[146:147], v[96:99], off nt
	v_lshl_add_u64 v[146:147], v[146:147], 0, s[38:39]
	global_store_dwordx4 v[146:147], v[88:91], off nt
	v_lshl_add_u64 v[146:147], v[146:147], 0, s[38:39]
	v_cvt_pk_bf16_f32 v76, v76, v77
	v_cvt_pk_bf16_f32 v77, v78, v79
	v_cvt_pk_bf16_f32 v78, v72, v73
	v_cvt_pk_bf16_f32 v79, v74, v75
	v_cvt_pk_bf16_f32 v68, v68, v69
	v_cvt_pk_bf16_f32 v69, v70, v71
	v_cvt_pk_bf16_f32 v70, v64, v65
	v_cvt_pk_bf16_f32 v71, v66, v67
	v_mov_b32_e32 v132, v76
	v_mov_b32_e32 v133, v77
	v_mov_b32_e32 v134, v78
	v_mov_b32_e32 v135, v79
	v_mov_b32_dpp v76, v68 row_ror:8 row_mask:0xf bank_mask:0xc
	v_mov_b32_dpp v77, v69 row_ror:8 row_mask:0xf bank_mask:0xc
	v_mov_b32_dpp v78, v70 row_ror:8 row_mask:0xf bank_mask:0xc
	v_mov_b32_dpp v79, v71 row_ror:8 row_mask:0xf bank_mask:0xc
	v_mov_b32_dpp v68, v132 row_ror:8 row_mask:0xf bank_mask:0x3
	v_mov_b32_dpp v69, v133 row_ror:8 row_mask:0xf bank_mask:0x3
	v_mov_b32_dpp v70, v134 row_ror:8 row_mask:0xf bank_mask:0x3
	v_mov_b32_dpp v71, v135 row_ror:8 row_mask:0xf bank_mask:0x3
	global_store_dwordx4 v[146:147], v[76:79], off nt
	v_lshl_add_u64 v[146:147], v[146:147], 0, s[38:39]
	global_store_dwordx4 v[146:147], v[68:71], off nt
	v_lshl_add_u64 v[146:147], v[146:147], 0, s[38:39]
	v_lshl_add_u64 v[146:147], v[146:147], 0, s[42:43]
	v_cvt_pk_bf16_f32 v60, v60, v61
	v_cvt_pk_bf16_f32 v61, v62, v63
	v_cvt_pk_bf16_f32 v62, v56, v57
	v_cvt_pk_bf16_f32 v63, v58, v59
	v_cvt_pk_bf16_f32 v52, v52, v53
	v_cvt_pk_bf16_f32 v53, v54, v55
	v_cvt_pk_bf16_f32 v54, v48, v49
	v_cvt_pk_bf16_f32 v55, v50, v51
	v_mov_b32_e32 v132, v60
	v_mov_b32_e32 v133, v61
	v_mov_b32_e32 v134, v62
	v_mov_b32_e32 v135, v63
	v_mov_b32_dpp v60, v52 row_ror:8 row_mask:0xf bank_mask:0xc
	v_mov_b32_dpp v61, v53 row_ror:8 row_mask:0xf bank_mask:0xc
	v_mov_b32_dpp v62, v54 row_ror:8 row_mask:0xf bank_mask:0xc
	v_mov_b32_dpp v63, v55 row_ror:8 row_mask:0xf bank_mask:0xc
	v_mov_b32_dpp v52, v132 row_ror:8 row_mask:0xf bank_mask:0x3
; DI unsigned pk2(float lo, float hi) { f32x2 v = {lo, hi}; bf16x2_t b = __builtin_convertvector(v, bf16x2_t); return __builtin_bit_cast(unsigned, b); }
; DI unsigned ror8(unsigned x) { return (unsigned)__builtin_amdgcn_mov_dpp((int)x, 0x128, 0xf, 0xf, true); }
; DI void store_lines(bf16_t* Ob, size_t row, int ldc, int colw, int fr, int fq, const u32x4& w0, const u32x4& w1) {
;     const bool lo = (fr & 8) == 0;
;     const u32x4 snd = lo ? w1 : w0;
;     u32x4 rcv; rcv.x = ror8(snd.x); rcv.y = ror8(snd.y); rcv.z = ror8(snd.z); rcv.w = ror8(snd.w);
;     const u32x4 dA = lo ? w0 : rcv, dB = lo ? rcv : w1;
;     const int col = colw + 8 * fq + (lo ? 0 : 32);
;     __builtin_nontemporal_store(dA, (u32x4*)(Ob + (lo ? row : row - 8) * ldc + col));
;     __builtin_nontemporal_store(dB, (u32x4*)(Ob + (lo ? row + 8 : row) * ldc + col));
; }
; DI void epilogue(const f32x4 (&acc)[2][2][4][2], int ph, unsigned char* ws, const float* pscale, const Unit& u, int wr, int wc, int fr, int fq) {
;     ...
;                     w[bj].x = pk2(v0[0], v0[1]); w[bj].y = pk2(v0[2], v0[3]); w[bj].z = pk2(v1[0], v1[1]); w[bj].w = pk2(v1[2], v1[3]); }
;                 store_lines(Ob, (size_t)(row0 + ai * HALF + m * 16), ldc, colw, fr, fq, w[0], w[1]); }
	v_mov_b32_dpp v53, v133 row_ror:8 row_mask:0xf bank_mask:0x3
	v_mov_b32_dpp v54, v134 row_ror:8 row_mask:0xf bank_mask:0x3
	v_mov_b32_dpp v55, v135 row_ror:8 row_mask:0xf bank_mask:0x3
	global_store_dwordx4 v[146:147], v[60:63], off nt
	v_lshl_add_u64 v[146:147], v[146:147], 0, s[38:39]
	global_store_dwordx4 v[146:147], v[52:55], off nt
	v_lshl_add_u64 v[146:147], v[146:147], 0, s[38:39]
	v_cvt_pk_bf16_f32 v44, v44, v45
	v_cvt_pk_bf16_f32 v45, v46, v47
	v_cvt_pk_bf16_f32 v46, v40, v41
	v_cvt_pk_bf16_f32 v47, v42, v43
	v_cvt_pk_bf16_f32 v36, v36, v37
	v_cvt_pk_bf16_f32 v37, v38, v39
	v_cvt_pk_bf16_f32 v38, v32, v33
	v_cvt_pk_bf16_f32 v39, v34, v35
	v_mov_b32_e32 v132, v44
	v_mov_b32_e32 v133, v45
	v_mov_b32_e32 v134, v46
	v_mov_b32_e32 v135, v47
	v_mov_b32_dpp v44, v36 row_ror:8 row_mask:0xf bank_mask:0xc
	v_mov_b32_dpp v45, v37 row_ror:8 row_mask:0xf bank_mask:0xc
	v_mov_b32_dpp v46, v38 row_ror:8 row_mask:0xf bank_mask:0xc
	v_mov_b32_dpp v47, v39 row_ror:8 row_mask:0xf bank_mask:0xc
	v_mov_b32_dpp v36, v132 row_ror:8 row_mask:0xf bank_mask:0x3
	v_mov_b32_dpp v37, v133 row_ror:8 row_mask:0xf bank_mask:0x3
	v_mov_b32_dpp v38, v134 row_ror:8 row_mask:0xf bank_mask:0x3
	v_mov_b32_dpp v39, v135 row_ror:8 row_mask:0xf bank_mask:0x3
	global_store_dwordx4 v[146:147], v[44:47], off nt
	v_lshl_add_u64 v[146:147], v[146:147], 0, s[38:39]
	global_store_dwordx4 v[146:147], v[36:39], off nt
	v_lshl_add_u64 v[146:147], v[146:147], 0, s[38:39]
	v_cvt_pk_bf16_f32 v28, v28, v29
	v_cvt_pk_bf16_f32 v29, v30, v31
	v_cvt_pk_bf16_f32 v30, v24, v25
	v_cvt_pk_bf16_f32 v31, v26, v27
	v_cvt_pk_bf16_f32 v20, v20, v21
	v_cvt_pk_bf16_f32 v21, v22, v23
	v_cvt_pk_bf16_f32 v22, v16, v17
	v_cvt_pk_bf16_f32 v23, v18, v19
	v_mov_b32_e32 v132, v28
	v_mov_b32_e32 v133, v29
	v_mov_b32_e32 v134, v30
	v_mov_b32_e32 v135, v31
	v_mov_b32_dpp v28, v20 row_ror:8 row_mask:0xf bank_mask:0xc
	v_mov_b32_dpp v29, v21 row_ror:8 row_mask:0xf bank_mask:0xc
	v_mov_b32_dpp v30, v22 row_ror:8 row_mask:0xf bank_mask:0xc
	v_mov_b32_dpp v31, v23 row_ror:8 row_mask:0xf bank_mask:0xc
	v_mov_b32_dpp v20, v132 row_ror:8 row_mask:0xf bank_mask:0x3
	v_mov_b32_dpp v21, v133 row_ror:8 row_mask:0xf bank_mask:0x3
	v_mov_b32_dpp v22, v134 row_ror:8 row_mask:0xf bank_mask:0x3
	v_mov_b32_dpp v23, v135 row_ror:8 row_mask:0xf bank_mask:0x3
	global_store_dwordx4 v[146:147], v[28:31], off nt
	v_lshl_add_u64 v[146:147], v[146:147], 0, s[38:39]
	global_store_dwordx4 v[146:147], v[20:23], off nt
	v_lshl_add_u64 v[146:147], v[146:147], 0, s[38:39]
	v_cvt_pk_bf16_f32 v12, v12, v13
	v_cvt_pk_bf16_f32 v13, v14, v15
	v_cvt_pk_bf16_f32 v14, v8, v9
	v_cvt_pk_bf16_f32 v15, v10, v11
	v_cvt_pk_bf16_f32 v4, v4, v5
	v_cvt_pk_bf16_f32 v5, v6, v7
	v_cvt_pk_bf16_f32 v6, v0, v1
	v_cvt_pk_bf16_f32 v7, v2, v3
	v_mov_b32_e32 v132, v12
	v_mov_b32_e32 v133, v13
	v_mov_b32_e32 v134, v14
	v_mov_b32_e32 v135, v15
	v_mov_b32_dpp v12, v4 row_ror:8 row_mask:0xf bank_mask:0xc
	v_mov_b32_dpp v13, v5 row_ror:8 row_mask:0xf bank_mask:0xc
	v_mov_b32_dpp v14, v6 row_ror:8 row_mask:0xf bank_mask:0xc
	v_mov_b32_dpp v15, v7 row_ror:8 row_mask:0xf bank_mask:0xc
	v_mov_b32_dpp v4, v132 row_ror:8 row_mask:0xf bank_mask:0x3
	v_mov_b32_dpp v5, v133 row_ror:8 row_mask:0xf bank_mask:0x3
	v_mov_b32_dpp v6, v134 row_ror:8 row_mask:0xf bank_mask:0x3
	v_mov_b32_dpp v7, v135 row_ror:8 row_mask:0xf bank_mask:0x3
	global_store_dwordx4 v[146:147], v[12:15], off nt
	v_lshl_add_u64 v[146:147], v[146:147], 0, s[38:39]
	global_store_dwordx4 v[146:147], v[4:7], off nt
	s_branch .LBB0_545
.LBB0_593:
	s_andn2_b64 vcc, exec, s[54:55]
	s_cbranch_vccnz .LBB0_466
	s_barrier
	s_branch .LBB0_466
.LBB0_619:
	s_endpgm
